# E-MFMA: SwiGLU epilogue of unit i embedded in the C=0 MFMA blocks of unit i+1's peeled first K-iteration (P1,P9), ALIGN barriers dropped for non-last units
# baseline (speedup 1.0000x reference)
.LBB0_268:
	v_add_u32_e32 v160, s43, v1
	ds_read_b128 v[156:159], v160
	ds_read_b128 v[162:165], v160 offset:1024
	ds_read_b128 v[166:169], v160 offset:2048
	ds_read_b128 v[170:173], v160 offset:3072
	v_add_u32_e32 v160, s44, v1
	ds_read_b128 v[174:177], v160
	ds_read_b128 v[178:181], v160 offset:1024
	ds_read_b128 v[182:185], v160 offset:2048
	ds_read_b128 v[192:195], v160 offset:3072
	s_add_u32 s52, s30, 0x10000
	s_addc_u32 s53, s31, 0
	s_cmp_eq_u32 s67, 12
	s_cselect_b32 s64, s51, s52
	s_cselect_b32 s65, s50, s53
	s_cselect_b32 s62, s55, s61
	s_cselect_b32 s63, s54, s66
	s_add_u32 s56, s64, 0x8000
	s_addc_u32 s57, s65, 0
	s_add_i32 m0, s36, 0xc000
	ds_read_b128 v[200:203], v155
	ds_read_b128 v[204:207], v155 offset:1024
	ds_read_b128 v[208:211], v155 offset:2048
	ds_read_b128 v[212:215], v155 offset:3072
	ds_read_b128 v[216:219], v155 offset:4096
	ds_read_b128 v[220:223], v155 offset:5120
	ds_read_b128 v[224:227], v155 offset:6144
	ds_read_b128 v[228:231], v155 offset:7168
	global_load_lds_dwordx4 v146, s[30:31] sc1
	s_add_i32 m0, s36, 0xe000
	s_nop 0
	global_load_lds_dwordx4 v148, s[30:31] sc1
	s_waitcnt vmcnt(8)
	s_waitcnt lgkmcnt(0)
	s_setprio 1
	s_barrier
	v_mfma_f32_16x16x32_bf16 v[118:121], v[156:159], v[200:203], v[118:121]
	v_mfma_f32_16x16x32_bf16 v[110:113], v[166:169], v[200:203], v[110:113]
	v_mfma_f32_16x16x32_bf16 v[102:105], v[156:159], v[208:211], v[102:105]
	v_mfma_f32_16x16x32_bf16 v[94:97], v[166:169], v[208:211], v[94:97]
	v_mfma_f32_16x16x32_bf16 v[86:89], v[156:159], v[216:219], v[86:89]
	v_mfma_f32_16x16x32_bf16 v[78:81], v[166:169], v[216:219], v[78:81]
	v_mfma_f32_16x16x32_bf16 v[62:65], v[156:159], v[224:227], v[62:65]
	v_mfma_f32_16x16x32_bf16 v[54:57], v[166:169], v[224:227], v[54:57]
	v_mfma_f32_16x16x32_bf16 v[118:121], v[162:165], v[204:207], v[118:121]
	v_mfma_f32_16x16x32_bf16 v[110:113], v[170:173], v[204:207], v[110:113]
	v_mfma_f32_16x16x32_bf16 v[102:105], v[162:165], v[212:215], v[102:105]
	v_mfma_f32_16x16x32_bf16 v[94:97], v[170:173], v[212:215], v[94:97]
	v_mfma_f32_16x16x32_bf16 v[86:89], v[162:165], v[220:223], v[86:89]
	v_mfma_f32_16x16x32_bf16 v[78:81], v[170:173], v[220:223], v[78:81]
	v_mfma_f32_16x16x32_bf16 v[62:65], v[162:165], v[228:231], v[62:65]
	v_mfma_f32_16x16x32_bf16 v[54:57], v[170:173], v[228:231], v[54:57]
	v_mfma_f32_16x16x32_bf16 v[126:129], v[174:177], v[200:203], v[126:129]
	v_mfma_f32_16x16x32_bf16 v[122:125], v[182:185], v[200:203], v[122:125]
	v_mfma_f32_16x16x32_bf16 v[114:117], v[174:177], v[208:211], v[114:117]
	v_mfma_f32_16x16x32_bf16 v[106:109], v[182:185], v[208:211], v[106:109]
	v_mfma_f32_16x16x32_bf16 v[98:101], v[174:177], v[216:219], v[98:101]
	v_mfma_f32_16x16x32_bf16 v[90:93], v[182:185], v[216:219], v[90:93]
	v_mfma_f32_16x16x32_bf16 v[82:85], v[174:177], v[224:227], v[82:85]
	v_mfma_f32_16x16x32_bf16 v[70:73], v[182:185], v[224:227], v[70:73]
	v_mfma_f32_16x16x32_bf16 v[126:129], v[178:181], v[204:207], v[126:129]
	v_mfma_f32_16x16x32_bf16 v[122:125], v[192:195], v[204:207], v[122:125]
	v_mfma_f32_16x16x32_bf16 v[114:117], v[178:181], v[212:215], v[114:117]
	v_mfma_f32_16x16x32_bf16 v[106:109], v[192:195], v[212:215], v[106:109]
	v_mfma_f32_16x16x32_bf16 v[98:101], v[178:181], v[220:223], v[98:101]
	v_mfma_f32_16x16x32_bf16 v[90:93], v[192:195], v[220:223], v[90:93]
	s_setprio 2
	s_barrier
	v_mfma_f32_16x16x32_bf16 v[82:85], v[178:181], v[228:231], v[82:85]
	v_mfma_f32_16x16x32_bf16 v[70:73], v[192:195], v[228:231], v[70:73]
	s_setprio 0
	s_add_i32 s30, s43, s5
	s_mov_b32 m0, s30
	ds_read_b128 v[200:203], v155 offset:16384
	ds_read_b128 v[204:207], v155 offset:17408
	ds_read_b128 v[208:211], v155 offset:18432
	ds_read_b128 v[212:215], v155 offset:19456
	ds_read_b128 v[216:219], v155 offset:20480
	ds_read_b128 v[220:223], v155 offset:21504
	ds_read_b128 v[224:227], v155 offset:22528
	ds_read_b128 v[228:231], v155 offset:23552
	global_load_lds_dwordx4 v134, s[62:63] sc1
	s_add_i32 m0, s30, 0x2000
	s_add_u32 s30, s62, 0x4000
	s_addc_u32 s31, s63, 0
	s_add_i32 s69, s44, s5
	global_load_lds_dwordx4 v136, s[62:63] sc1
	s_mov_b32 m0, s69
	s_nop 0
	global_load_lds_dwordx4 v134, s[30:31] sc1
	s_add_i32 m0, s69, 0x2000
	s_nop 0
	global_load_lds_dwordx4 v136, s[30:31] sc1
	s_mov_b32 m0, s36
	s_nop 0
	global_load_lds_dwordx4 v132, s[64:65] sc1
	s_mov_b32 m0, s37
	s_nop 0
	global_load_lds_dwordx4 v130, s[64:65] sc1
	s_waitcnt vmcnt(8)
	s_waitcnt lgkmcnt(0)
	s_setprio 1
	s_barrier
	v_mfma_f32_16x16x32_bf16 v[58:61], v[156:159], v[200:203], v[58:61]
	v_mfma_f32_16x16x32_bf16 v[46:49], v[166:169], v[200:203], v[46:49]
	v_mfma_f32_16x16x32_bf16 v[38:41], v[156:159], v[208:211], v[38:41]
	v_mfma_f32_16x16x32_bf16 v[30:33], v[166:169], v[208:211], v[30:33]
	v_mfma_f32_16x16x32_bf16 v[22:25], v[156:159], v[216:219], v[22:25]
	v_mfma_f32_16x16x32_bf16 v[14:17], v[166:169], v[216:219], v[14:17]
	v_mfma_f32_16x16x32_bf16 v[6:9], v[156:159], v[224:227], v[6:9]
	v_mfma_f32_16x16x32_bf16 v[2:5], v[166:169], v[224:227], v[2:5]
	v_mfma_f32_16x16x32_bf16 v[58:61], v[162:165], v[204:207], v[58:61]
	v_mfma_f32_16x16x32_bf16 v[46:49], v[170:173], v[204:207], v[46:49]
	v_mfma_f32_16x16x32_bf16 v[38:41], v[162:165], v[212:215], v[38:41]
	v_mfma_f32_16x16x32_bf16 v[30:33], v[170:173], v[212:215], v[30:33]
	v_mfma_f32_16x16x32_bf16 v[22:25], v[162:165], v[220:223], v[22:25]
	v_mfma_f32_16x16x32_bf16 v[14:17], v[170:173], v[220:223], v[14:17]
	v_mfma_f32_16x16x32_bf16 v[6:9], v[162:165], v[228:231], v[6:9]
	v_mfma_f32_16x16x32_bf16 v[2:5], v[170:173], v[228:231], v[2:5]
	v_mfma_f32_16x16x32_bf16 v[74:77], v[174:177], v[200:203], v[74:77]
	v_mfma_f32_16x16x32_bf16 v[66:69], v[182:185], v[200:203], v[66:69]
	v_mfma_f32_16x16x32_bf16 v[50:53], v[174:177], v[208:211], v[50:53]
	v_mfma_f32_16x16x32_bf16 v[42:45], v[182:185], v[208:211], v[42:45]
	v_mfma_f32_16x16x32_bf16 v[34:37], v[174:177], v[216:219], v[34:37]
	v_mfma_f32_16x16x32_bf16 v[26:29], v[182:185], v[216:219], v[26:29]
	v_mfma_f32_16x16x32_bf16 v[18:21], v[174:177], v[224:227], v[18:21]
	v_mfma_f32_16x16x32_bf16 v[10:13], v[182:185], v[224:227], v[10:13]
	v_mfma_f32_16x16x32_bf16 v[74:77], v[178:181], v[204:207], v[74:77]
	v_mfma_f32_16x16x32_bf16 v[66:69], v[192:195], v[204:207], v[66:69]
	v_mfma_f32_16x16x32_bf16 v[50:53], v[178:181], v[212:215], v[50:53]
	v_mfma_f32_16x16x32_bf16 v[42:45], v[192:195], v[212:215], v[42:45]
	v_mfma_f32_16x16x32_bf16 v[34:37], v[178:181], v[220:223], v[34:37]
	v_mfma_f32_16x16x32_bf16 v[26:29], v[192:195], v[220:223], v[26:29]
	s_setprio 2
	s_barrier
	v_mfma_f32_16x16x32_bf16 v[18:21], v[178:181], v[228:231], v[18:21]
	v_mfma_f32_16x16x32_bf16 v[10:13], v[192:195], v[228:231], v[10:13]
	s_setprio 0
	v_add_u32_e32 v160, s45, v1
	ds_read_b128 v[156:159], v160
	ds_read_b128 v[162:165], v160 offset:1024
	ds_read_b128 v[166:169], v160 offset:2048
	ds_read_b128 v[170:173], v160 offset:3072
	v_add_u32_e32 v160, s46, v1
	ds_read_b128 v[174:177], v160
	ds_read_b128 v[178:181], v160 offset:1024
	ds_read_b128 v[182:185], v160 offset:2048
	ds_read_b128 v[192:195], v160 offset:3072
	s_add_u32 s30, s64, 0x4000
	s_addc_u32 s31, s65, 0
	s_mov_b32 m0, s38
	ds_read_b128 v[200:203], v155 offset:32768
	ds_read_b128 v[204:207], v155 offset:33792
	ds_read_b128 v[208:211], v155 offset:34816
	ds_read_b128 v[212:215], v155 offset:35840
	ds_read_b128 v[216:219], v155 offset:36864
	ds_read_b128 v[220:223], v155 offset:37888
	ds_read_b128 v[224:227], v155 offset:38912
	ds_read_b128 v[228:231], v155 offset:39936
	global_load_lds_dwordx4 v132, s[30:31] sc1
	s_mov_b32 m0, s39
	s_nop 0
	global_load_lds_dwordx4 v130, s[30:31] sc1
	s_waitcnt vmcnt(8)
	s_waitcnt lgkmcnt(0)
	s_setprio 1
	s_barrier
	v_mfma_f32_16x16x32_bf16 v[118:121], v[156:159], v[200:203], v[118:121]
	v_mfma_f32_16x16x32_bf16 v[110:113], v[166:169], v[200:203], v[110:113]
	v_mfma_f32_16x16x32_bf16 v[102:105], v[156:159], v[208:211], v[102:105]
	v_mfma_f32_16x16x32_bf16 v[94:97], v[166:169], v[208:211], v[94:97]
	v_mfma_f32_16x16x32_bf16 v[86:89], v[156:159], v[216:219], v[86:89]
	v_mfma_f32_16x16x32_bf16 v[78:81], v[166:169], v[216:219], v[78:81]
	v_mfma_f32_16x16x32_bf16 v[62:65], v[156:159], v[224:227], v[62:65]
	v_mfma_f32_16x16x32_bf16 v[54:57], v[166:169], v[224:227], v[54:57]
	v_mfma_f32_16x16x32_bf16 v[118:121], v[162:165], v[204:207], v[118:121]
	v_mfma_f32_16x16x32_bf16 v[110:113], v[170:173], v[204:207], v[110:113]
	v_mfma_f32_16x16x32_bf16 v[102:105], v[162:165], v[212:215], v[102:105]
	v_mfma_f32_16x16x32_bf16 v[94:97], v[170:173], v[212:215], v[94:97]
	v_mfma_f32_16x16x32_bf16 v[86:89], v[162:165], v[220:223], v[86:89]
	v_mfma_f32_16x16x32_bf16 v[78:81], v[170:173], v[220:223], v[78:81]
	v_mfma_f32_16x16x32_bf16 v[62:65], v[162:165], v[228:231], v[62:65]
	v_mfma_f32_16x16x32_bf16 v[54:57], v[170:173], v[228:231], v[54:57]
	v_mfma_f32_16x16x32_bf16 v[126:129], v[174:177], v[200:203], v[126:129]
	v_mfma_f32_16x16x32_bf16 v[122:125], v[182:185], v[200:203], v[122:125]
	v_mfma_f32_16x16x32_bf16 v[114:117], v[174:177], v[208:211], v[114:117]
	v_mfma_f32_16x16x32_bf16 v[106:109], v[182:185], v[208:211], v[106:109]
	v_mfma_f32_16x16x32_bf16 v[98:101], v[174:177], v[216:219], v[98:101]
	v_mfma_f32_16x16x32_bf16 v[90:93], v[182:185], v[216:219], v[90:93]
	v_mfma_f32_16x16x32_bf16 v[82:85], v[174:177], v[224:227], v[82:85]
	v_mfma_f32_16x16x32_bf16 v[70:73], v[182:185], v[224:227], v[70:73]
	v_mfma_f32_16x16x32_bf16 v[126:129], v[178:181], v[204:207], v[126:129]
	v_mfma_f32_16x16x32_bf16 v[122:125], v[192:195], v[204:207], v[122:125]
	v_mfma_f32_16x16x32_bf16 v[114:117], v[178:181], v[212:215], v[114:117]
	v_mfma_f32_16x16x32_bf16 v[106:109], v[192:195], v[212:215], v[106:109]
	v_mfma_f32_16x16x32_bf16 v[98:101], v[178:181], v[220:223], v[98:101]
	v_mfma_f32_16x16x32_bf16 v[90:93], v[192:195], v[220:223], v[90:93]
	s_setprio 2
	s_barrier
	v_mfma_f32_16x16x32_bf16 v[82:85], v[178:181], v[228:231], v[82:85]
	v_mfma_f32_16x16x32_bf16 v[70:73], v[192:195], v[228:231], v[70:73]
	s_setprio 0
	s_add_u32 s30, s62, 0x8000
	s_addc_u32 s31, s63, 0
	s_add_i32 s64, s45, s5
	s_mov_b32 m0, s64
	ds_read_b128 v[200:203], v155 offset:49152
	ds_read_b128 v[204:207], v155 offset:50176
	ds_read_b128 v[208:211], v155 offset:51200
	ds_read_b128 v[212:215], v155 offset:52224
	ds_read_b128 v[216:219], v155 offset:53248
	ds_read_b128 v[220:223], v155 offset:54272
	ds_read_b128 v[224:227], v155 offset:55296
	ds_read_b128 v[228:231], v155 offset:56320
	global_load_lds_dwordx4 v134, s[30:31] sc1
	s_add_i32 m0, s64, 0x2000
	s_nop 0
	global_load_lds_dwordx4 v136, s[30:31] sc1
	s_add_u32 s30, s62, 0xc000
	s_addc_u32 s31, s63, 0
	s_add_i32 s62, s46, s5
	s_mov_b32 m0, s62
	s_nop 0
	global_load_lds_dwordx4 v134, s[30:31] sc1
	s_add_i32 m0, s62, 0x2000
	s_nop 0
	global_load_lds_dwordx4 v136, s[30:31] sc1
	s_mov_b32 m0, s40
	s_nop 0
	global_load_lds_dwordx4 v132, s[56:57] sc1
	s_mov_b32 m0, s41
	s_nop 0
	global_load_lds_dwordx4 v130, s[56:57] sc1
	s_waitcnt vmcnt(8)
	s_waitcnt lgkmcnt(0)
	s_setprio 1
	s_barrier
	v_mfma_f32_16x16x32_bf16 v[58:61], v[156:159], v[200:203], v[58:61]
	v_mfma_f32_16x16x32_bf16 v[46:49], v[166:169], v[200:203], v[46:49]
	v_mfma_f32_16x16x32_bf16 v[38:41], v[156:159], v[208:211], v[38:41]
	v_mfma_f32_16x16x32_bf16 v[30:33], v[166:169], v[208:211], v[30:33]
	v_mfma_f32_16x16x32_bf16 v[22:25], v[156:159], v[216:219], v[22:25]
	v_mfma_f32_16x16x32_bf16 v[14:17], v[166:169], v[216:219], v[14:17]
	v_mfma_f32_16x16x32_bf16 v[6:9], v[156:159], v[224:227], v[6:9]
	v_mfma_f32_16x16x32_bf16 v[2:5], v[166:169], v[224:227], v[2:5]
	v_mfma_f32_16x16x32_bf16 v[58:61], v[162:165], v[204:207], v[58:61]
	v_mfma_f32_16x16x32_bf16 v[46:49], v[170:173], v[204:207], v[46:49]
	v_mfma_f32_16x16x32_bf16 v[38:41], v[162:165], v[212:215], v[38:41]
	v_mfma_f32_16x16x32_bf16 v[30:33], v[170:173], v[212:215], v[30:33]
	v_mfma_f32_16x16x32_bf16 v[22:25], v[162:165], v[220:223], v[22:25]
	v_mfma_f32_16x16x32_bf16 v[14:17], v[170:173], v[220:223], v[14:17]
	v_mfma_f32_16x16x32_bf16 v[6:9], v[162:165], v[228:231], v[6:9]
	v_mfma_f32_16x16x32_bf16 v[2:5], v[170:173], v[228:231], v[2:5]
	v_mfma_f32_16x16x32_bf16 v[74:77], v[174:177], v[200:203], v[74:77]
	v_mfma_f32_16x16x32_bf16 v[66:69], v[182:185], v[200:203], v[66:69]
	v_mfma_f32_16x16x32_bf16 v[50:53], v[174:177], v[208:211], v[50:53]
	v_mfma_f32_16x16x32_bf16 v[42:45], v[182:185], v[208:211], v[42:45]
	v_mfma_f32_16x16x32_bf16 v[34:37], v[174:177], v[216:219], v[34:37]
	v_mfma_f32_16x16x32_bf16 v[26:29], v[182:185], v[216:219], v[26:29]
	v_mfma_f32_16x16x32_bf16 v[18:21], v[174:177], v[224:227], v[18:21]
	v_mfma_f32_16x16x32_bf16 v[10:13], v[182:185], v[224:227], v[10:13]
	v_mfma_f32_16x16x32_bf16 v[74:77], v[178:181], v[204:207], v[74:77]
	v_mfma_f32_16x16x32_bf16 v[66:69], v[192:195], v[204:207], v[66:69]
	v_mfma_f32_16x16x32_bf16 v[50:53], v[178:181], v[212:215], v[50:53]
	v_mfma_f32_16x16x32_bf16 v[42:45], v[192:195], v[212:215], v[42:45]
	v_mfma_f32_16x16x32_bf16 v[34:37], v[178:181], v[220:223], v[34:37]
	v_mfma_f32_16x16x32_bf16 v[26:29], v[192:195], v[220:223], v[26:29]
	s_setprio 2
	s_barrier
	v_mfma_f32_16x16x32_bf16 v[18:21], v[178:181], v[228:231], v[18:21]
	v_mfma_f32_16x16x32_bf16 v[10:13], v[192:195], v[228:231], v[10:13]
	s_setprio 0
	s_add_i32 s67, s67, 2
	s_add_u32 s61, s61, 0x10000
	s_addc_u32 s66, s66, 0
	s_cmp_gt_u32 s67, 13
	s_mov_b64 s[30:31], s[52:53]
	s_cbranch_scc0 .LBB0_268
	s_cmp_eq_u32 s49, s59
	s_cbranch_scc1 .Lemb0_last
	s_mov_b32 s98, s49
	s_mov_b32 s49, s35
	s_add_i32 s35, s35, 1
	s_cmp_lt_u32 s35, s15
	s_mov_b64 s[30:31], s[28:29]
	s_mov_b32 s28, s48
	s_cselect_b64 s[54:55], -1, 0
	s_add_i32 s48, s35, s4
	s_mov_b64 s[52:53], s[6:7]
	s_and_b64 s[6:7], s[54:55], exec
	s_cselect_b32 s6, s48, s28
	s_cselect_b32 s28, s58, s58
	s_ashr_i32 s29, s28, 31
	s_lshl_b64 s[28:29], s[28:29], 19
	s_add_u32 s28, s60, s28
	s_addc_u32 s29, s33, s29
	s_and_b64 s[50:51], s[54:55], exec
	s_cselect_b32 s50, s29, s31
	s_cselect_b32 s51, s28, s30
	s_ashr_i32 s7, s6, 31
	s_lshl_b64 s[6:7], s[6:7], 19
	s_add_u32 s6, s86, s6
	s_addc_u32 s7, s87, s7
	s_and_b64 s[54:55], s[54:55], exec
	s_cselect_b32 s54, s7, s53
	s_cselect_b32 s55, s6, s52
	s_add_u32 s61, s52, 0x10000
	s_addc_u32 s66, s53, 0
	s_mov_b32 s67, -2
	v_add_u32_e32 v160, s43, v1
	ds_read_b128 v[156:159], v160
	ds_read_b128 v[162:165], v160 offset:1024
	ds_read_b128 v[166:169], v160 offset:2048
	ds_read_b128 v[170:173], v160 offset:3072
	v_add_u32_e32 v160, s44, v1
	ds_read_b128 v[174:177], v160
	ds_read_b128 v[178:181], v160 offset:1024
	ds_read_b128 v[182:185], v160 offset:2048
	ds_read_b128 v[192:195], v160 offset:3072
	s_add_u32 s52, s30, 0x10000
	s_addc_u32 s53, s31, 0
	s_cmp_eq_u32 s67, 12
	s_cselect_b32 s64, s51, s52
	s_cselect_b32 s65, s50, s53
	s_cselect_b32 s62, s55, s61
	s_cselect_b32 s63, s54, s66
	s_add_u32 s56, s64, 0x8000
	s_addc_u32 s57, s65, 0
	s_add_i32 m0, s36, 0xc000
	ds_read_b128 v[200:203], v155
	ds_read_b128 v[204:207], v155 offset:1024
	ds_read_b128 v[208:211], v155 offset:2048
	ds_read_b128 v[212:215], v155 offset:3072
	ds_read_b128 v[216:219], v155 offset:4096
	ds_read_b128 v[220:223], v155 offset:5120
	ds_read_b128 v[224:227], v155 offset:6144
	ds_read_b128 v[228:231], v155 offset:7168
	v_lshl_add_u32 v199, s98, 10, v154
	ds_read_b32 v186, v199
	ds_read_b32 v187, v199 offset:64
	ds_read_b32 v196, v199 offset:128
	ds_read_b32 v197, v199 offset:192
	global_load_lds_dwordx4 v146, s[30:31] sc1
	s_add_i32 m0, s36, 0xe000
	s_nop 0
	global_load_lds_dwordx4 v148, s[30:31] sc1
	s_waitcnt vmcnt(8)
	s_waitcnt lgkmcnt(0)
	s_setprio 1
	s_barrier
	s_add_i32 s99, s98, s4
	s_lshl_b32 s99, s99, 15
	s_or_b32 s99, s99, s47
	s_and_b32 s99, s99, 0xffffc000
	s_add_i32 s100, s99, s42
	v_mul_f32_e32 v248, 0xbfb8aa3b, v186
	v_mul_f32_e32 v249, v186, v186
	v_rcp_f32_e32 v250, v249
	v_pk_mul_f32 v[232:233], v[118:119], v[248:249] op_sel_hi:[1,0]
	v_pk_mul_f32 v[234:235], v[120:121], v[248:249] op_sel_hi:[1,0]
	v_pk_mul_f32 v[236:237], v[110:111], v[248:249] op_sel_hi:[1,0]
	v_pk_mul_f32 v[238:239], v[112:113], v[248:249] op_sel_hi:[1,0]
	v_pk_mul_f32 v[240:241], v[118:119], v[126:127]
	v_pk_mul_f32 v[242:243], v[120:121], v[128:129]
	v_pk_mul_f32 v[244:245], v[110:111], v[122:123]
	v_pk_mul_f32 v[246:247], v[112:113], v[124:125]
	v_exp_f32_e32 v232, v232
	v_exp_f32_e32 v233, v233
	v_exp_f32_e32 v234, v234
	v_exp_f32_e32 v235, v235
	v_mfma_f32_16x16x32_bf16 v[118:121], v[156:159], v[200:203], 0
	v_exp_f32_e32 v236, v236
	v_exp_f32_e32 v237, v237
	v_exp_f32_e32 v238, v238
	v_exp_f32_e32 v239, v239
	v_mfma_f32_16x16x32_bf16 v[110:113], v[166:169], v[200:203], 0
	v_fma_f32 v232, v232, v250, v250
	v_fma_f32 v233, v233, v250, v250
	v_fma_f32 v234, v234, v250, v250
	v_fma_f32 v235, v235, v250, v250
	v_mfma_f32_16x16x32_bf16 v[126:129], v[174:177], v[200:203], 0
	v_fma_f32 v236, v236, v250, v250
	v_fma_f32 v237, v237, v250, v250
	v_fma_f32 v238, v238, v250, v250
	v_fma_f32 v239, v239, v250, v250
	v_mfma_f32_16x16x32_bf16 v[122:125], v[182:185], v[200:203], 0
	v_rcp_f32_e32 v232, v232
	v_rcp_f32_e32 v233, v233
	v_rcp_f32_e32 v234, v234
	v_rcp_f32_e32 v235, v235
	v_mfma_f32_16x16x32_bf16 v[118:121], v[162:165], v[204:207], v[118:121]
	v_rcp_f32_e32 v236, v236
	v_rcp_f32_e32 v237, v237
	v_rcp_f32_e32 v238, v238
	v_rcp_f32_e32 v239, v239
	v_mfma_f32_16x16x32_bf16 v[110:113], v[170:173], v[204:207], v[110:113]
	v_or_b32_e32 v251, s100, v139
	v_lshlrev_b32_e32 v251, 1, v251
	v_pk_mul_f32 v[240:241], v[240:241], v[232:233]
	v_pk_mul_f32 v[242:243], v[242:243], v[234:235]
	v_mfma_f32_16x16x32_bf16 v[126:129], v[178:181], v[204:207], v[126:129]
	v_pk_mul_f32 v[244:245], v[244:245], v[236:237]
	v_pk_mul_f32 v[246:247], v[246:247], v[238:239]
	v_cvt_pk_bf16_f32 v232, v240, v241
	v_cvt_pk_bf16_f32 v233, v242, v243
	v_mfma_f32_16x16x32_bf16 v[122:125], v[192:195], v[204:207], v[122:125]
	v_cvt_pk_bf16_f32 v234, v244, v245
	v_cvt_pk_bf16_f32 v235, v246, v247
	buffer_store_dwordx4 v[232:235], v251, s[72:75], 0 offen sc1
	v_mul_f32_e32 v248, 0xbfb8aa3b, v187
	v_mul_f32_e32 v249, v187, v187
	v_rcp_f32_e32 v250, v249
	v_pk_mul_f32 v[232:233], v[102:103], v[248:249] op_sel_hi:[1,0]
	v_pk_mul_f32 v[234:235], v[104:105], v[248:249] op_sel_hi:[1,0]
	v_pk_mul_f32 v[236:237], v[94:95], v[248:249] op_sel_hi:[1,0]
	v_pk_mul_f32 v[238:239], v[96:97], v[248:249] op_sel_hi:[1,0]
	v_pk_mul_f32 v[240:241], v[102:103], v[114:115]
	v_pk_mul_f32 v[242:243], v[104:105], v[116:117]
	v_pk_mul_f32 v[244:245], v[94:95], v[106:107]
	v_pk_mul_f32 v[246:247], v[96:97], v[108:109]
	v_exp_f32_e32 v232, v232
	v_exp_f32_e32 v233, v233
	v_exp_f32_e32 v234, v234
	v_exp_f32_e32 v235, v235
	v_mfma_f32_16x16x32_bf16 v[102:105], v[156:159], v[208:211], 0
	v_exp_f32_e32 v236, v236
	v_exp_f32_e32 v237, v237
	v_exp_f32_e32 v238, v238
	v_exp_f32_e32 v239, v239
	v_mfma_f32_16x16x32_bf16 v[94:97], v[166:169], v[208:211], 0
	v_fma_f32 v232, v232, v250, v250
	v_fma_f32 v233, v233, v250, v250
	v_fma_f32 v234, v234, v250, v250
	v_fma_f32 v235, v235, v250, v250
	v_mfma_f32_16x16x32_bf16 v[114:117], v[174:177], v[208:211], 0
	v_fma_f32 v236, v236, v250, v250
	v_fma_f32 v237, v237, v250, v250
	v_fma_f32 v238, v238, v250, v250
	v_fma_f32 v239, v239, v250, v250
	v_mfma_f32_16x16x32_bf16 v[106:109], v[182:185], v[208:211], 0
	v_rcp_f32_e32 v232, v232
	v_rcp_f32_e32 v233, v233
	v_rcp_f32_e32 v234, v234
	v_rcp_f32_e32 v235, v235
	v_mfma_f32_16x16x32_bf16 v[102:105], v[162:165], v[212:215], v[102:105]
	v_rcp_f32_e32 v236, v236
	v_rcp_f32_e32 v237, v237
	v_rcp_f32_e32 v238, v238
	v_rcp_f32_e32 v239, v239
	v_mfma_f32_16x16x32_bf16 v[94:97], v[170:173], v[212:215], v[94:97]
	v_or_b32_e32 v251, s100, v141
	v_lshlrev_b32_e32 v251, 1, v251
	v_pk_mul_f32 v[240:241], v[240:241], v[232:233]
	v_pk_mul_f32 v[242:243], v[242:243], v[234:235]
	v_mfma_f32_16x16x32_bf16 v[114:117], v[178:181], v[212:215], v[114:117]
	v_pk_mul_f32 v[244:245], v[244:245], v[236:237]
	v_pk_mul_f32 v[246:247], v[246:247], v[238:239]
	v_cvt_pk_bf16_f32 v232, v240, v241
	v_cvt_pk_bf16_f32 v233, v242, v243
	v_mfma_f32_16x16x32_bf16 v[106:109], v[192:195], v[212:215], v[106:109]
	v_cvt_pk_bf16_f32 v234, v244, v245
	v_cvt_pk_bf16_f32 v235, v246, v247
	buffer_store_dwordx4 v[232:235], v251, s[72:75], 0 offen sc1
	v_mul_f32_e32 v248, 0xbfb8aa3b, v196
	v_mul_f32_e32 v249, v196, v196
	v_rcp_f32_e32 v250, v249
	v_pk_mul_f32 v[232:233], v[86:87], v[248:249] op_sel_hi:[1,0]
	v_pk_mul_f32 v[234:235], v[88:89], v[248:249] op_sel_hi:[1,0]
	v_pk_mul_f32 v[236:237], v[78:79], v[248:249] op_sel_hi:[1,0]
	v_pk_mul_f32 v[238:239], v[80:81], v[248:249] op_sel_hi:[1,0]
	v_pk_mul_f32 v[240:241], v[86:87], v[98:99]
	v_pk_mul_f32 v[242:243], v[88:89], v[100:101]
	v_pk_mul_f32 v[244:245], v[78:79], v[90:91]
	v_pk_mul_f32 v[246:247], v[80:81], v[92:93]
	v_exp_f32_e32 v232, v232
	v_exp_f32_e32 v233, v233
	v_exp_f32_e32 v234, v234
	v_exp_f32_e32 v235, v235
	v_mfma_f32_16x16x32_bf16 v[86:89], v[156:159], v[216:219], 0
	v_exp_f32_e32 v236, v236
	v_exp_f32_e32 v237, v237
	v_exp_f32_e32 v238, v238
	v_exp_f32_e32 v239, v239
	v_mfma_f32_16x16x32_bf16 v[78:81], v[166:169], v[216:219], 0
	v_fma_f32 v232, v232, v250, v250
	v_fma_f32 v233, v233, v250, v250
	v_fma_f32 v234, v234, v250, v250
	v_fma_f32 v235, v235, v250, v250
	v_mfma_f32_16x16x32_bf16 v[98:101], v[174:177], v[216:219], 0
	v_fma_f32 v236, v236, v250, v250
	v_fma_f32 v237, v237, v250, v250
	v_fma_f32 v238, v238, v250, v250
	v_fma_f32 v239, v239, v250, v250
	v_mfma_f32_16x16x32_bf16 v[90:93], v[182:185], v[216:219], 0
	v_rcp_f32_e32 v232, v232
	v_rcp_f32_e32 v233, v233
	v_rcp_f32_e32 v234, v234
	v_rcp_f32_e32 v235, v235
	v_mfma_f32_16x16x32_bf16 v[86:89], v[162:165], v[220:223], v[86:89]
	v_rcp_f32_e32 v236, v236
	v_rcp_f32_e32 v237, v237
	v_rcp_f32_e32 v238, v238
	v_rcp_f32_e32 v239, v239
	v_mfma_f32_16x16x32_bf16 v[78:81], v[170:173], v[220:223], v[78:81]
	v_or_b32_e32 v251, s100, v143
	v_lshlrev_b32_e32 v251, 1, v251
	v_pk_mul_f32 v[240:241], v[240:241], v[232:233]
	v_pk_mul_f32 v[242:243], v[242:243], v[234:235]
	v_mfma_f32_16x16x32_bf16 v[98:101], v[178:181], v[220:223], v[98:101]
	v_pk_mul_f32 v[244:245], v[244:245], v[236:237]
	v_pk_mul_f32 v[246:247], v[246:247], v[238:239]
	v_cvt_pk_bf16_f32 v232, v240, v241
	v_cvt_pk_bf16_f32 v233, v242, v243
	v_mfma_f32_16x16x32_bf16 v[90:93], v[192:195], v[220:223], v[90:93]
	v_cvt_pk_bf16_f32 v234, v244, v245
	v_cvt_pk_bf16_f32 v235, v246, v247
	buffer_store_dwordx4 v[232:235], v251, s[72:75], 0 offen sc1
	v_mul_f32_e32 v248, 0xbfb8aa3b, v197
	v_mul_f32_e32 v249, v197, v197
	v_rcp_f32_e32 v250, v249
	v_pk_mul_f32 v[232:233], v[62:63], v[248:249] op_sel_hi:[1,0]
	v_pk_mul_f32 v[234:235], v[64:65], v[248:249] op_sel_hi:[1,0]
	v_pk_mul_f32 v[236:237], v[54:55], v[248:249] op_sel_hi:[1,0]
	v_pk_mul_f32 v[238:239], v[56:57], v[248:249] op_sel_hi:[1,0]
	v_pk_mul_f32 v[240:241], v[62:63], v[82:83]
	v_pk_mul_f32 v[242:243], v[64:65], v[84:85]
	v_pk_mul_f32 v[244:245], v[54:55], v[70:71]
	v_pk_mul_f32 v[246:247], v[56:57], v[72:73]
	v_exp_f32_e32 v232, v232
	v_exp_f32_e32 v233, v233
	v_exp_f32_e32 v234, v234
	v_exp_f32_e32 v235, v235
	v_mfma_f32_16x16x32_bf16 v[62:65], v[156:159], v[224:227], 0
	v_exp_f32_e32 v236, v236
	v_exp_f32_e32 v237, v237
	v_exp_f32_e32 v238, v238
	v_exp_f32_e32 v239, v239
	v_mfma_f32_16x16x32_bf16 v[54:57], v[166:169], v[224:227], 0
	v_fma_f32 v232, v232, v250, v250
	v_fma_f32 v233, v233, v250, v250
	v_fma_f32 v234, v234, v250, v250
	v_fma_f32 v235, v235, v250, v250
	v_mfma_f32_16x16x32_bf16 v[82:85], v[174:177], v[224:227], 0
	v_fma_f32 v236, v236, v250, v250
	v_fma_f32 v237, v237, v250, v250
	v_fma_f32 v238, v238, v250, v250
	v_fma_f32 v239, v239, v250, v250
	v_mfma_f32_16x16x32_bf16 v[70:73], v[182:185], v[224:227], 0
	v_rcp_f32_e32 v232, v232
	v_rcp_f32_e32 v233, v233
	v_rcp_f32_e32 v234, v234
	v_rcp_f32_e32 v235, v235
	v_mfma_f32_16x16x32_bf16 v[62:65], v[162:165], v[228:231], v[62:65]
	v_rcp_f32_e32 v236, v236
	v_rcp_f32_e32 v237, v237
	v_rcp_f32_e32 v238, v238
	v_rcp_f32_e32 v239, v239
	v_mfma_f32_16x16x32_bf16 v[54:57], v[170:173], v[228:231], v[54:57]
	v_or_b32_e32 v251, s100, v145
	v_lshlrev_b32_e32 v251, 1, v251
	v_pk_mul_f32 v[240:241], v[240:241], v[232:233]
	v_pk_mul_f32 v[242:243], v[242:243], v[234:235]
	v_pk_mul_f32 v[244:245], v[244:245], v[236:237]
	v_pk_mul_f32 v[246:247], v[246:247], v[238:239]
	v_cvt_pk_bf16_f32 v232, v240, v241
	v_cvt_pk_bf16_f32 v233, v242, v243
	v_cvt_pk_bf16_f32 v234, v244, v245
	v_cvt_pk_bf16_f32 v235, v246, v247
	buffer_store_dwordx4 v[232:235], v251, s[72:75], 0 offen sc1
	s_setprio 2
	s_barrier
	v_mfma_f32_16x16x32_bf16 v[82:85], v[178:181], v[228:231], v[82:85]
	v_mfma_f32_16x16x32_bf16 v[70:73], v[192:195], v[228:231], v[70:73]
	s_setprio 0
	s_add_i32 s30, s43, s5
	s_mov_b32 m0, s30
	ds_read_b128 v[200:203], v155 offset:16384
	ds_read_b128 v[204:207], v155 offset:17408
	ds_read_b128 v[208:211], v155 offset:18432
	ds_read_b128 v[212:215], v155 offset:19456
	ds_read_b128 v[216:219], v155 offset:20480
	ds_read_b128 v[220:223], v155 offset:21504
	ds_read_b128 v[224:227], v155 offset:22528
	ds_read_b128 v[228:231], v155 offset:23552
	ds_read_b32 v186, v199 offset:512
	ds_read_b32 v187, v199 offset:576
	ds_read_b32 v196, v199 offset:640
	ds_read_b32 v197, v199 offset:704
	global_load_lds_dwordx4 v134, s[62:63] sc1
	s_add_i32 m0, s30, 0x2000
	s_add_u32 s30, s62, 0x4000
	s_addc_u32 s31, s63, 0
	s_add_i32 s69, s44, s5
	global_load_lds_dwordx4 v136, s[62:63] sc1
	s_mov_b32 m0, s69
	s_nop 0
	global_load_lds_dwordx4 v134, s[30:31] sc1
	s_add_i32 m0, s69, 0x2000
	s_nop 0
	global_load_lds_dwordx4 v136, s[30:31] sc1
	s_mov_b32 m0, s36
	s_nop 0
	global_load_lds_dwordx4 v132, s[64:65] sc1
	s_mov_b32 m0, s37
	s_nop 0
	global_load_lds_dwordx4 v130, s[64:65] sc1
	s_waitcnt vmcnt(12)
	s_waitcnt lgkmcnt(0)
	s_setprio 1
	s_barrier
	v_mul_f32_e32 v248, 0xbfb8aa3b, v186
	v_mul_f32_e32 v249, v186, v186
	v_rcp_f32_e32 v250, v249
	v_pk_mul_f32 v[232:233], v[58:59], v[248:249] op_sel_hi:[1,0]
	v_pk_mul_f32 v[234:235], v[60:61], v[248:249] op_sel_hi:[1,0]
	v_pk_mul_f32 v[236:237], v[46:47], v[248:249] op_sel_hi:[1,0]
	v_pk_mul_f32 v[238:239], v[48:49], v[248:249] op_sel_hi:[1,0]
	v_pk_mul_f32 v[240:241], v[58:59], v[74:75]
	v_pk_mul_f32 v[242:243], v[60:61], v[76:77]
	v_pk_mul_f32 v[244:245], v[46:47], v[66:67]
	v_pk_mul_f32 v[246:247], v[48:49], v[68:69]
	v_exp_f32_e32 v232, v232
	v_exp_f32_e32 v233, v233
	v_exp_f32_e32 v234, v234
	v_exp_f32_e32 v235, v235
	v_mfma_f32_16x16x32_bf16 v[58:61], v[156:159], v[200:203], 0
	v_exp_f32_e32 v236, v236
	v_exp_f32_e32 v237, v237
	v_exp_f32_e32 v238, v238
	v_exp_f32_e32 v239, v239
	v_mfma_f32_16x16x32_bf16 v[46:49], v[166:169], v[200:203], 0
	v_fma_f32 v232, v232, v250, v250
	v_fma_f32 v233, v233, v250, v250
	v_fma_f32 v234, v234, v250, v250
	v_fma_f32 v235, v235, v250, v250
	v_mfma_f32_16x16x32_bf16 v[74:77], v[174:177], v[200:203], 0
	v_fma_f32 v236, v236, v250, v250
	v_fma_f32 v237, v237, v250, v250
	v_fma_f32 v238, v238, v250, v250
	v_fma_f32 v239, v239, v250, v250
	v_mfma_f32_16x16x32_bf16 v[66:69], v[182:185], v[200:203], 0
	v_rcp_f32_e32 v232, v232
	v_rcp_f32_e32 v233, v233
	v_rcp_f32_e32 v234, v234
	v_rcp_f32_e32 v235, v235
	v_mfma_f32_16x16x32_bf16 v[58:61], v[162:165], v[204:207], v[58:61]
	v_rcp_f32_e32 v236, v236
	v_rcp_f32_e32 v237, v237
	v_rcp_f32_e32 v238, v238
	v_rcp_f32_e32 v239, v239
	v_mfma_f32_16x16x32_bf16 v[46:49], v[170:173], v[204:207], v[46:49]
	v_add_u32_e32 v251, s99, v138
	v_or_b32_e32 v251, v251, v150
	v_lshlrev_b32_e32 v251, 1, v251
	v_pk_mul_f32 v[240:241], v[240:241], v[232:233]
	v_mfma_f32_16x16x32_bf16 v[74:77], v[178:181], v[204:207], v[74:77]
	v_pk_mul_f32 v[242:243], v[242:243], v[234:235]
	v_pk_mul_f32 v[244:245], v[244:245], v[236:237]
	v_pk_mul_f32 v[246:247], v[246:247], v[238:239]
	v_cvt_pk_bf16_f32 v232, v240, v241
	v_mfma_f32_16x16x32_bf16 v[66:69], v[192:195], v[204:207], v[66:69]
	v_cvt_pk_bf16_f32 v233, v242, v243
	v_cvt_pk_bf16_f32 v234, v244, v245
	v_cvt_pk_bf16_f32 v235, v246, v247
	buffer_store_dwordx4 v[232:235], v251, s[72:75], 0 offen sc1
	v_mul_f32_e32 v248, 0xbfb8aa3b, v187
	v_mul_f32_e32 v249, v187, v187
	v_rcp_f32_e32 v250, v249
	v_pk_mul_f32 v[232:233], v[38:39], v[248:249] op_sel_hi:[1,0]
	v_pk_mul_f32 v[234:235], v[40:41], v[248:249] op_sel_hi:[1,0]
	v_pk_mul_f32 v[236:237], v[30:31], v[248:249] op_sel_hi:[1,0]
	v_pk_mul_f32 v[238:239], v[32:33], v[248:249] op_sel_hi:[1,0]
	v_pk_mul_f32 v[240:241], v[38:39], v[50:51]
	v_pk_mul_f32 v[242:243], v[40:41], v[52:53]
	v_pk_mul_f32 v[244:245], v[30:31], v[42:43]
	v_pk_mul_f32 v[246:247], v[32:33], v[44:45]
	v_exp_f32_e32 v232, v232
	v_exp_f32_e32 v233, v233
	v_exp_f32_e32 v234, v234
	v_exp_f32_e32 v235, v235
	v_mfma_f32_16x16x32_bf16 v[38:41], v[156:159], v[208:211], 0
	v_exp_f32_e32 v236, v236
	v_exp_f32_e32 v237, v237
	v_exp_f32_e32 v238, v238
	v_exp_f32_e32 v239, v239
	v_mfma_f32_16x16x32_bf16 v[30:33], v[166:169], v[208:211], 0
	v_fma_f32 v232, v232, v250, v250
	v_fma_f32 v233, v233, v250, v250
	v_fma_f32 v234, v234, v250, v250
	v_fma_f32 v235, v235, v250, v250
	v_mfma_f32_16x16x32_bf16 v[50:53], v[174:177], v[208:211], 0
	v_fma_f32 v236, v236, v250, v250
	v_fma_f32 v237, v237, v250, v250
	v_fma_f32 v238, v238, v250, v250
	v_fma_f32 v239, v239, v250, v250
	v_mfma_f32_16x16x32_bf16 v[42:45], v[182:185], v[208:211], 0
	v_rcp_f32_e32 v232, v232
	v_rcp_f32_e32 v233, v233
	v_rcp_f32_e32 v234, v234
	v_rcp_f32_e32 v235, v235
	v_mfma_f32_16x16x32_bf16 v[38:41], v[162:165], v[212:215], v[38:41]
	v_rcp_f32_e32 v236, v236
	v_rcp_f32_e32 v237, v237
	v_rcp_f32_e32 v238, v238
	v_rcp_f32_e32 v239, v239
	v_mfma_f32_16x16x32_bf16 v[30:33], v[170:173], v[212:215], v[30:33]
	v_add_u32_e32 v251, s99, v140
	v_or_b32_e32 v251, v251, v151
	v_lshlrev_b32_e32 v251, 1, v251
	v_pk_mul_f32 v[240:241], v[240:241], v[232:233]
	v_mfma_f32_16x16x32_bf16 v[50:53], v[178:181], v[212:215], v[50:53]
	v_pk_mul_f32 v[242:243], v[242:243], v[234:235]
	v_pk_mul_f32 v[244:245], v[244:245], v[236:237]
	v_pk_mul_f32 v[246:247], v[246:247], v[238:239]
	v_cvt_pk_bf16_f32 v232, v240, v241
	v_mfma_f32_16x16x32_bf16 v[42:45], v[192:195], v[212:215], v[42:45]
	v_cvt_pk_bf16_f32 v233, v242, v243
	v_cvt_pk_bf16_f32 v234, v244, v245
	v_cvt_pk_bf16_f32 v235, v246, v247
	buffer_store_dwordx4 v[232:235], v251, s[72:75], 0 offen sc1
	v_mul_f32_e32 v248, 0xbfb8aa3b, v196
	v_mul_f32_e32 v249, v196, v196
	v_rcp_f32_e32 v250, v249
	v_pk_mul_f32 v[232:233], v[22:23], v[248:249] op_sel_hi:[1,0]
	v_pk_mul_f32 v[234:235], v[24:25], v[248:249] op_sel_hi:[1,0]
	v_pk_mul_f32 v[236:237], v[14:15], v[248:249] op_sel_hi:[1,0]
	v_pk_mul_f32 v[238:239], v[16:17], v[248:249] op_sel_hi:[1,0]
	v_pk_mul_f32 v[240:241], v[22:23], v[34:35]
	v_pk_mul_f32 v[242:243], v[24:25], v[36:37]
	v_pk_mul_f32 v[244:245], v[14:15], v[26:27]
	v_pk_mul_f32 v[246:247], v[16:17], v[28:29]
	v_exp_f32_e32 v232, v232
	v_exp_f32_e32 v233, v233
	v_exp_f32_e32 v234, v234
	v_exp_f32_e32 v235, v235
	v_mfma_f32_16x16x32_bf16 v[22:25], v[156:159], v[216:219], 0
	v_exp_f32_e32 v236, v236
	v_exp_f32_e32 v237, v237
	v_exp_f32_e32 v238, v238
	v_exp_f32_e32 v239, v239
	v_mfma_f32_16x16x32_bf16 v[14:17], v[166:169], v[216:219], 0
	v_fma_f32 v232, v232, v250, v250
	v_fma_f32 v233, v233, v250, v250
	v_fma_f32 v234, v234, v250, v250
	v_fma_f32 v235, v235, v250, v250
	v_mfma_f32_16x16x32_bf16 v[34:37], v[174:177], v[216:219], 0
	v_fma_f32 v236, v236, v250, v250
	v_fma_f32 v237, v237, v250, v250
	v_fma_f32 v238, v238, v250, v250
	v_fma_f32 v239, v239, v250, v250
	v_mfma_f32_16x16x32_bf16 v[26:29], v[182:185], v[216:219], 0
	v_rcp_f32_e32 v232, v232
	v_rcp_f32_e32 v233, v233
	v_rcp_f32_e32 v234, v234
	v_rcp_f32_e32 v235, v235
	v_mfma_f32_16x16x32_bf16 v[22:25], v[162:165], v[220:223], v[22:25]
	v_rcp_f32_e32 v236, v236
	v_rcp_f32_e32 v237, v237
	v_rcp_f32_e32 v238, v238
	v_rcp_f32_e32 v239, v239
	v_mfma_f32_16x16x32_bf16 v[14:17], v[170:173], v[220:223], v[14:17]
	v_add_u32_e32 v251, s99, v142
	v_or_b32_e32 v251, v251, v152
	v_lshlrev_b32_e32 v251, 1, v251
	v_pk_mul_f32 v[240:241], v[240:241], v[232:233]
	v_mfma_f32_16x16x32_bf16 v[34:37], v[178:181], v[220:223], v[34:37]
	v_pk_mul_f32 v[242:243], v[242:243], v[234:235]
	v_pk_mul_f32 v[244:245], v[244:245], v[236:237]
	v_pk_mul_f32 v[246:247], v[246:247], v[238:239]
	v_cvt_pk_bf16_f32 v232, v240, v241
	v_mfma_f32_16x16x32_bf16 v[26:29], v[192:195], v[220:223], v[26:29]
	v_cvt_pk_bf16_f32 v233, v242, v243
	v_cvt_pk_bf16_f32 v234, v244, v245
	v_cvt_pk_bf16_f32 v235, v246, v247
	buffer_store_dwordx4 v[232:235], v251, s[72:75], 0 offen sc1
	v_mul_f32_e32 v248, 0xbfb8aa3b, v197
	v_mul_f32_e32 v249, v197, v197
	v_rcp_f32_e32 v250, v249
	v_pk_mul_f32 v[232:233], v[6:7], v[248:249] op_sel_hi:[1,0]
	v_pk_mul_f32 v[234:235], v[8:9], v[248:249] op_sel_hi:[1,0]
	v_pk_mul_f32 v[236:237], v[2:3], v[248:249] op_sel_hi:[1,0]
	v_pk_mul_f32 v[238:239], v[4:5], v[248:249] op_sel_hi:[1,0]
	v_pk_mul_f32 v[240:241], v[6:7], v[18:19]
	v_pk_mul_f32 v[242:243], v[8:9], v[20:21]
	v_pk_mul_f32 v[244:245], v[2:3], v[10:11]
	v_pk_mul_f32 v[246:247], v[4:5], v[12:13]
	v_exp_f32_e32 v232, v232
	v_exp_f32_e32 v233, v233
	v_exp_f32_e32 v234, v234
	v_exp_f32_e32 v235, v235
	v_mfma_f32_16x16x32_bf16 v[6:9], v[156:159], v[224:227], 0
	v_exp_f32_e32 v236, v236
	v_exp_f32_e32 v237, v237
	v_exp_f32_e32 v238, v238
	v_exp_f32_e32 v239, v239
	v_mfma_f32_16x16x32_bf16 v[2:5], v[166:169], v[224:227], 0
	v_fma_f32 v232, v232, v250, v250
	v_fma_f32 v233, v233, v250, v250
	v_fma_f32 v234, v234, v250, v250
	v_fma_f32 v235, v235, v250, v250
	v_mfma_f32_16x16x32_bf16 v[18:21], v[174:177], v[224:227], 0
	v_fma_f32 v236, v236, v250, v250
	v_fma_f32 v237, v237, v250, v250
	v_fma_f32 v238, v238, v250, v250
	v_fma_f32 v239, v239, v250, v250
	v_mfma_f32_16x16x32_bf16 v[10:13], v[182:185], v[224:227], 0
	v_rcp_f32_e32 v232, v232
	v_rcp_f32_e32 v233, v233
	v_rcp_f32_e32 v234, v234
	v_rcp_f32_e32 v235, v235
	v_mfma_f32_16x16x32_bf16 v[6:9], v[162:165], v[228:231], v[6:9]
	v_rcp_f32_e32 v236, v236
	v_rcp_f32_e32 v237, v237
	v_rcp_f32_e32 v238, v238
	v_rcp_f32_e32 v239, v239
	v_mfma_f32_16x16x32_bf16 v[2:5], v[170:173], v[228:231], v[2:5]
	v_add_u32_e32 v251, s99, v144
	v_or_b32_e32 v251, v251, v153
	v_lshlrev_b32_e32 v251, 1, v251
	v_pk_mul_f32 v[240:241], v[240:241], v[232:233]
	v_pk_mul_f32 v[242:243], v[242:243], v[234:235]
	v_pk_mul_f32 v[244:245], v[244:245], v[236:237]
	v_pk_mul_f32 v[246:247], v[246:247], v[238:239]
	v_cvt_pk_bf16_f32 v232, v240, v241
	v_cvt_pk_bf16_f32 v233, v242, v243
	v_cvt_pk_bf16_f32 v234, v244, v245
	v_cvt_pk_bf16_f32 v235, v246, v247
	buffer_store_dwordx4 v[232:235], v251, s[72:75], 0 offen sc1
	s_setprio 2
	s_barrier
	v_mfma_f32_16x16x32_bf16 v[18:21], v[178:181], v[228:231], v[18:21]
	v_mfma_f32_16x16x32_bf16 v[10:13], v[192:195], v[228:231], v[10:13]
	s_setprio 0
	v_add_u32_e32 v160, s45, v1
	ds_read_b128 v[156:159], v160
	ds_read_b128 v[162:165], v160 offset:1024
	ds_read_b128 v[166:169], v160 offset:2048
	ds_read_b128 v[170:173], v160 offset:3072
	v_add_u32_e32 v160, s46, v1
	ds_read_b128 v[174:177], v160
	ds_read_b128 v[178:181], v160 offset:1024
	ds_read_b128 v[182:185], v160 offset:2048
	ds_read_b128 v[192:195], v160 offset:3072
	s_add_u32 s30, s64, 0x4000
	s_addc_u32 s31, s65, 0
	s_mov_b32 m0, s38
	ds_read_b128 v[200:203], v155 offset:32768
	ds_read_b128 v[204:207], v155 offset:33792
	ds_read_b128 v[208:211], v155 offset:34816
	ds_read_b128 v[212:215], v155 offset:35840
	ds_read_b128 v[216:219], v155 offset:36864
	ds_read_b128 v[220:223], v155 offset:37888
	ds_read_b128 v[224:227], v155 offset:38912
	ds_read_b128 v[228:231], v155 offset:39936
	global_load_lds_dwordx4 v132, s[30:31] sc1
	s_mov_b32 m0, s39
	s_nop 0
	global_load_lds_dwordx4 v130, s[30:31] sc1
	s_waitcnt vmcnt(16)
	s_waitcnt lgkmcnt(0)
	s_setprio 1
	s_barrier
	v_mfma_f32_16x16x32_bf16 v[118:121], v[156:159], v[200:203], v[118:121]
	v_mfma_f32_16x16x32_bf16 v[110:113], v[166:169], v[200:203], v[110:113]
	v_mfma_f32_16x16x32_bf16 v[102:105], v[156:159], v[208:211], v[102:105]
	v_mfma_f32_16x16x32_bf16 v[94:97], v[166:169], v[208:211], v[94:97]
	v_mfma_f32_16x16x32_bf16 v[86:89], v[156:159], v[216:219], v[86:89]
	v_mfma_f32_16x16x32_bf16 v[78:81], v[166:169], v[216:219], v[78:81]
	v_mfma_f32_16x16x32_bf16 v[62:65], v[156:159], v[224:227], v[62:65]
	v_mfma_f32_16x16x32_bf16 v[54:57], v[166:169], v[224:227], v[54:57]
	v_mfma_f32_16x16x32_bf16 v[118:121], v[162:165], v[204:207], v[118:121]
	v_mfma_f32_16x16x32_bf16 v[110:113], v[170:173], v[204:207], v[110:113]
	v_mfma_f32_16x16x32_bf16 v[102:105], v[162:165], v[212:215], v[102:105]
	v_mfma_f32_16x16x32_bf16 v[94:97], v[170:173], v[212:215], v[94:97]
	v_mfma_f32_16x16x32_bf16 v[86:89], v[162:165], v[220:223], v[86:89]
	v_mfma_f32_16x16x32_bf16 v[78:81], v[170:173], v[220:223], v[78:81]
	v_mfma_f32_16x16x32_bf16 v[62:65], v[162:165], v[228:231], v[62:65]
	v_mfma_f32_16x16x32_bf16 v[54:57], v[170:173], v[228:231], v[54:57]
	v_mfma_f32_16x16x32_bf16 v[126:129], v[174:177], v[200:203], v[126:129]
	v_mfma_f32_16x16x32_bf16 v[122:125], v[182:185], v[200:203], v[122:125]
	v_mfma_f32_16x16x32_bf16 v[114:117], v[174:177], v[208:211], v[114:117]
	v_mfma_f32_16x16x32_bf16 v[106:109], v[182:185], v[208:211], v[106:109]
	v_mfma_f32_16x16x32_bf16 v[98:101], v[174:177], v[216:219], v[98:101]
	v_mfma_f32_16x16x32_bf16 v[90:93], v[182:185], v[216:219], v[90:93]
	v_mfma_f32_16x16x32_bf16 v[82:85], v[174:177], v[224:227], v[82:85]
	v_mfma_f32_16x16x32_bf16 v[70:73], v[182:185], v[224:227], v[70:73]
	v_mfma_f32_16x16x32_bf16 v[126:129], v[178:181], v[204:207], v[126:129]
	v_mfma_f32_16x16x32_bf16 v[122:125], v[192:195], v[204:207], v[122:125]
	v_mfma_f32_16x16x32_bf16 v[114:117], v[178:181], v[212:215], v[114:117]
	v_mfma_f32_16x16x32_bf16 v[106:109], v[192:195], v[212:215], v[106:109]
	v_mfma_f32_16x16x32_bf16 v[98:101], v[178:181], v[220:223], v[98:101]
	v_mfma_f32_16x16x32_bf16 v[90:93], v[192:195], v[220:223], v[90:93]
	s_setprio 2
	s_barrier
	v_mfma_f32_16x16x32_bf16 v[82:85], v[178:181], v[228:231], v[82:85]
	v_mfma_f32_16x16x32_bf16 v[70:73], v[192:195], v[228:231], v[70:73]
	s_setprio 0
	s_add_u32 s30, s62, 0x8000
	s_addc_u32 s31, s63, 0
	s_add_i32 s64, s45, s5
	s_mov_b32 m0, s64
	ds_read_b128 v[200:203], v155 offset:49152
	ds_read_b128 v[204:207], v155 offset:50176
	ds_read_b128 v[208:211], v155 offset:51200
	ds_read_b128 v[212:215], v155 offset:52224
	ds_read_b128 v[216:219], v155 offset:53248
	ds_read_b128 v[220:223], v155 offset:54272
	ds_read_b128 v[224:227], v155 offset:55296
	ds_read_b128 v[228:231], v155 offset:56320
	global_load_lds_dwordx4 v134, s[30:31] sc1
	s_add_i32 m0, s64, 0x2000
	s_nop 0
	global_load_lds_dwordx4 v136, s[30:31] sc1
	s_add_u32 s30, s62, 0xc000
	s_addc_u32 s31, s63, 0
	s_add_i32 s62, s46, s5
	s_mov_b32 m0, s62
	s_nop 0
	global_load_lds_dwordx4 v134, s[30:31] sc1
	s_add_i32 m0, s62, 0x2000
	s_nop 0
	global_load_lds_dwordx4 v136, s[30:31] sc1
	s_mov_b32 m0, s40
	s_nop 0
	global_load_lds_dwordx4 v132, s[56:57] sc1
	s_mov_b32 m0, s41
	s_nop 0
	global_load_lds_dwordx4 v130, s[56:57] sc1
	s_waitcnt vmcnt(12)
	s_waitcnt lgkmcnt(0)
	s_setprio 1
	s_barrier
	v_mfma_f32_16x16x32_bf16 v[58:61], v[156:159], v[200:203], v[58:61]
	v_mfma_f32_16x16x32_bf16 v[46:49], v[166:169], v[200:203], v[46:49]
	v_mfma_f32_16x16x32_bf16 v[38:41], v[156:159], v[208:211], v[38:41]
	v_mfma_f32_16x16x32_bf16 v[30:33], v[166:169], v[208:211], v[30:33]
	v_mfma_f32_16x16x32_bf16 v[22:25], v[156:159], v[216:219], v[22:25]
	v_mfma_f32_16x16x32_bf16 v[14:17], v[166:169], v[216:219], v[14:17]
	v_mfma_f32_16x16x32_bf16 v[6:9], v[156:159], v[224:227], v[6:9]
	v_mfma_f32_16x16x32_bf16 v[2:5], v[166:169], v[224:227], v[2:5]
	v_mfma_f32_16x16x32_bf16 v[58:61], v[162:165], v[204:207], v[58:61]
	v_mfma_f32_16x16x32_bf16 v[46:49], v[170:173], v[204:207], v[46:49]
	v_mfma_f32_16x16x32_bf16 v[38:41], v[162:165], v[212:215], v[38:41]
	v_mfma_f32_16x16x32_bf16 v[30:33], v[170:173], v[212:215], v[30:33]
	v_mfma_f32_16x16x32_bf16 v[22:25], v[162:165], v[220:223], v[22:25]
	v_mfma_f32_16x16x32_bf16 v[14:17], v[170:173], v[220:223], v[14:17]
	v_mfma_f32_16x16x32_bf16 v[6:9], v[162:165], v[228:231], v[6:9]
	v_mfma_f32_16x16x32_bf16 v[2:5], v[170:173], v[228:231], v[2:5]
	v_mfma_f32_16x16x32_bf16 v[74:77], v[174:177], v[200:203], v[74:77]
	v_mfma_f32_16x16x32_bf16 v[66:69], v[182:185], v[200:203], v[66:69]
	v_mfma_f32_16x16x32_bf16 v[50:53], v[174:177], v[208:211], v[50:53]
	v_mfma_f32_16x16x32_bf16 v[42:45], v[182:185], v[208:211], v[42:45]
	v_mfma_f32_16x16x32_bf16 v[34:37], v[174:177], v[216:219], v[34:37]
	v_mfma_f32_16x16x32_bf16 v[26:29], v[182:185], v[216:219], v[26:29]
	v_mfma_f32_16x16x32_bf16 v[18:21], v[174:177], v[224:227], v[18:21]
	v_mfma_f32_16x16x32_bf16 v[10:13], v[182:185], v[224:227], v[10:13]
	v_mfma_f32_16x16x32_bf16 v[74:77], v[178:181], v[204:207], v[74:77]
	v_mfma_f32_16x16x32_bf16 v[66:69], v[192:195], v[204:207], v[66:69]
	v_mfma_f32_16x16x32_bf16 v[50:53], v[178:181], v[212:215], v[50:53]
	v_mfma_f32_16x16x32_bf16 v[42:45], v[192:195], v[212:215], v[42:45]
	v_mfma_f32_16x16x32_bf16 v[34:37], v[178:181], v[220:223], v[34:37]
	v_mfma_f32_16x16x32_bf16 v[26:29], v[192:195], v[220:223], v[26:29]
	s_setprio 2
	s_barrier
	v_mfma_f32_16x16x32_bf16 v[18:21], v[178:181], v[228:231], v[18:21]
	v_mfma_f32_16x16x32_bf16 v[10:13], v[192:195], v[228:231], v[10:13]
	s_setprio 0
	s_add_i32 s67, s67, 2
	s_add_u32 s61, s61, 0x10000
	s_addc_u32 s66, s66, 0
	s_cmp_gt_u32 s67, 13
	s_mov_b64 s[30:31], s[52:53]
	s_branch .LBB0_268
.Lemb0_last:
	s_and_b64 vcc, exec, s[10:11]
	s_cbranch_vccz .LBB0_271
	s_barrier

.LBB0_1093:
	v_add_u32_e32 v155, s47, v148
	ds_read_b128 v[156:159], v155
	ds_read_b128 v[160:163], v155 offset:1024
	ds_read_b128 v[164:167], v155 offset:2048
	ds_read_b128 v[168:171], v155 offset:3072
	v_add_u32_e32 v155, s48, v148
	ds_read_b128 v[172:175], v155
	ds_read_b128 v[176:179], v155 offset:1024
	ds_read_b128 v[180:183], v155 offset:2048
	ds_read_b128 v[184:187], v155 offset:3072
	s_add_u32 s40, s18, 0x10000
	s_addc_u32 s41, s19, 0
	s_cmp_eq_u32 s78, 12
	s_cselect_b32 s64, s69, s40
	s_cselect_b32 s65, s55, s41
	s_cselect_b32 s62, s71, s76
	s_cselect_b32 s63, s70, s77
	s_add_u32 s56, s64, 0x8000
	s_addc_u32 s57, s65, 0
	s_add_i32 m0, s37, 0xc000
	ds_read_b128 v[192:195], v154
	ds_read_b128 v[200:203], v154 offset:1024
	ds_read_b128 v[204:207], v154 offset:2048
	ds_read_b128 v[208:211], v154 offset:3072
	ds_read_b128 v[212:215], v154 offset:4096
	ds_read_b128 v[216:219], v154 offset:5120
	ds_read_b128 v[220:223], v154 offset:6144
	ds_read_b128 v[224:227], v154 offset:7168
	global_load_lds_dwordx4 v144, s[18:19] sc1
	s_add_i32 m0, s37, 0xe000
	s_nop 0
	global_load_lds_dwordx4 v146, s[18:19] sc1
	s_waitcnt vmcnt(8)
	s_waitcnt lgkmcnt(0)
	s_setprio 1
	s_barrier
	v_mfma_f32_16x16x32_bf16 v[116:119], v[156:159], v[192:195], v[116:119]
	v_mfma_f32_16x16x32_bf16 v[108:111], v[164:167], v[192:195], v[108:111]
	v_mfma_f32_16x16x32_bf16 v[100:103], v[156:159], v[204:207], v[100:103]
	v_mfma_f32_16x16x32_bf16 v[92:95], v[164:167], v[204:207], v[92:95]
	v_mfma_f32_16x16x32_bf16 v[84:87], v[156:159], v[212:215], v[84:87]
	v_mfma_f32_16x16x32_bf16 v[76:79], v[164:167], v[212:215], v[76:79]
	v_mfma_f32_16x16x32_bf16 v[60:63], v[156:159], v[220:223], v[60:63]
	v_mfma_f32_16x16x32_bf16 v[52:55], v[164:167], v[220:223], v[52:55]
	v_mfma_f32_16x16x32_bf16 v[116:119], v[160:163], v[200:203], v[116:119]
	v_mfma_f32_16x16x32_bf16 v[108:111], v[168:171], v[200:203], v[108:111]
	v_mfma_f32_16x16x32_bf16 v[100:103], v[160:163], v[208:211], v[100:103]
	v_mfma_f32_16x16x32_bf16 v[92:95], v[168:171], v[208:211], v[92:95]
	v_mfma_f32_16x16x32_bf16 v[84:87], v[160:163], v[216:219], v[84:87]
	v_mfma_f32_16x16x32_bf16 v[76:79], v[168:171], v[216:219], v[76:79]
	v_mfma_f32_16x16x32_bf16 v[60:63], v[160:163], v[224:227], v[60:63]
	v_mfma_f32_16x16x32_bf16 v[52:55], v[168:171], v[224:227], v[52:55]
	v_mfma_f32_16x16x32_bf16 v[124:127], v[172:175], v[192:195], v[124:127]
	v_mfma_f32_16x16x32_bf16 v[120:123], v[180:183], v[192:195], v[120:123]
	v_mfma_f32_16x16x32_bf16 v[112:115], v[172:175], v[204:207], v[112:115]
	v_mfma_f32_16x16x32_bf16 v[104:107], v[180:183], v[204:207], v[104:107]
	v_mfma_f32_16x16x32_bf16 v[96:99], v[172:175], v[212:215], v[96:99]
	v_mfma_f32_16x16x32_bf16 v[88:91], v[180:183], v[212:215], v[88:91]
	v_mfma_f32_16x16x32_bf16 v[80:83], v[172:175], v[220:223], v[80:83]
	v_mfma_f32_16x16x32_bf16 v[68:71], v[180:183], v[220:223], v[68:71]
	v_mfma_f32_16x16x32_bf16 v[124:127], v[176:179], v[200:203], v[124:127]
	v_mfma_f32_16x16x32_bf16 v[120:123], v[184:187], v[200:203], v[120:123]
	v_mfma_f32_16x16x32_bf16 v[112:115], v[176:179], v[208:211], v[112:115]
	v_mfma_f32_16x16x32_bf16 v[104:107], v[184:187], v[208:211], v[104:107]
	v_mfma_f32_16x16x32_bf16 v[96:99], v[176:179], v[216:219], v[96:99]
	v_mfma_f32_16x16x32_bf16 v[88:91], v[184:187], v[216:219], v[88:91]
	s_setprio 2
	s_barrier
	v_mfma_f32_16x16x32_bf16 v[80:83], v[176:179], v[224:227], v[80:83]
	v_mfma_f32_16x16x32_bf16 v[68:71], v[184:187], v[224:227], v[68:71]
	s_setprio 0
	s_add_i32 s18, s47, s36
	s_mov_b32 m0, s18
	ds_read_b128 v[192:195], v154 offset:16384
	ds_read_b128 v[200:203], v154 offset:17408
	ds_read_b128 v[204:207], v154 offset:18432
	ds_read_b128 v[208:211], v154 offset:19456
	ds_read_b128 v[212:215], v154 offset:20480
	ds_read_b128 v[216:219], v154 offset:21504
	ds_read_b128 v[220:223], v154 offset:22528
	ds_read_b128 v[224:227], v154 offset:23552
	global_load_lds_dwordx4 v132, s[62:63] sc1
	s_add_i32 m0, s18, 0x2000
	s_add_u32 s18, s62, 0x4000
	s_addc_u32 s19, s63, 0
	s_add_i32 s79, s48, s36
	global_load_lds_dwordx4 v134, s[62:63] sc1
	s_mov_b32 m0, s79
	s_nop 0
	global_load_lds_dwordx4 v132, s[18:19] sc1
	s_add_i32 m0, s79, 0x2000
	s_nop 0
	global_load_lds_dwordx4 v134, s[18:19] sc1
	s_mov_b32 m0, s37
	s_nop 0
	global_load_lds_dwordx4 v130, s[64:65] sc1
	s_mov_b32 m0, s42
	s_nop 0
	global_load_lds_dwordx4 v128, s[64:65] sc1
	s_waitcnt vmcnt(8)
	s_waitcnt lgkmcnt(0)
	s_setprio 1
	s_barrier
	v_mfma_f32_16x16x32_bf16 v[56:59], v[156:159], v[192:195], v[56:59]
	v_mfma_f32_16x16x32_bf16 v[44:47], v[164:167], v[192:195], v[44:47]
	v_mfma_f32_16x16x32_bf16 v[36:39], v[156:159], v[204:207], v[36:39]
	v_mfma_f32_16x16x32_bf16 v[28:31], v[164:167], v[204:207], v[28:31]
	v_mfma_f32_16x16x32_bf16 v[20:23], v[156:159], v[212:215], v[20:23]
	v_mfma_f32_16x16x32_bf16 v[12:15], v[164:167], v[212:215], v[12:15]
	v_mfma_f32_16x16x32_bf16 v[4:7], v[156:159], v[220:223], v[4:7]
	v_mfma_f32_16x16x32_bf16 v[0:3], v[164:167], v[220:223], v[0:3]
	v_mfma_f32_16x16x32_bf16 v[56:59], v[160:163], v[200:203], v[56:59]
	v_mfma_f32_16x16x32_bf16 v[44:47], v[168:171], v[200:203], v[44:47]
	v_mfma_f32_16x16x32_bf16 v[36:39], v[160:163], v[208:211], v[36:39]
	v_mfma_f32_16x16x32_bf16 v[28:31], v[168:171], v[208:211], v[28:31]
	v_mfma_f32_16x16x32_bf16 v[20:23], v[160:163], v[216:219], v[20:23]
	v_mfma_f32_16x16x32_bf16 v[12:15], v[168:171], v[216:219], v[12:15]
	v_mfma_f32_16x16x32_bf16 v[4:7], v[160:163], v[224:227], v[4:7]
	v_mfma_f32_16x16x32_bf16 v[0:3], v[168:171], v[224:227], v[0:3]
	v_mfma_f32_16x16x32_bf16 v[72:75], v[172:175], v[192:195], v[72:75]
	v_mfma_f32_16x16x32_bf16 v[64:67], v[180:183], v[192:195], v[64:67]
	v_mfma_f32_16x16x32_bf16 v[48:51], v[172:175], v[204:207], v[48:51]
	v_mfma_f32_16x16x32_bf16 v[40:43], v[180:183], v[204:207], v[40:43]
	v_mfma_f32_16x16x32_bf16 v[32:35], v[172:175], v[212:215], v[32:35]
	v_mfma_f32_16x16x32_bf16 v[24:27], v[180:183], v[212:215], v[24:27]
	v_mfma_f32_16x16x32_bf16 v[16:19], v[172:175], v[220:223], v[16:19]
	v_mfma_f32_16x16x32_bf16 v[8:11], v[180:183], v[220:223], v[8:11]
	v_mfma_f32_16x16x32_bf16 v[72:75], v[176:179], v[200:203], v[72:75]
	v_mfma_f32_16x16x32_bf16 v[64:67], v[184:187], v[200:203], v[64:67]
	v_mfma_f32_16x16x32_bf16 v[48:51], v[176:179], v[208:211], v[48:51]
	v_mfma_f32_16x16x32_bf16 v[40:43], v[184:187], v[208:211], v[40:43]
	v_mfma_f32_16x16x32_bf16 v[32:35], v[176:179], v[216:219], v[32:35]
	v_mfma_f32_16x16x32_bf16 v[24:27], v[184:187], v[216:219], v[24:27]
	s_setprio 2
	s_barrier
	v_mfma_f32_16x16x32_bf16 v[16:19], v[176:179], v[224:227], v[16:19]
	v_mfma_f32_16x16x32_bf16 v[8:11], v[184:187], v[224:227], v[8:11]
	s_setprio 0
	v_add_u32_e32 v155, s49, v148
	ds_read_b128 v[156:159], v155
	ds_read_b128 v[160:163], v155 offset:1024
	ds_read_b128 v[164:167], v155 offset:2048
	ds_read_b128 v[168:171], v155 offset:3072
	v_add_u32_e32 v155, s50, v148
	ds_read_b128 v[172:175], v155
	ds_read_b128 v[176:179], v155 offset:1024
	ds_read_b128 v[180:183], v155 offset:2048
	ds_read_b128 v[184:187], v155 offset:3072
	s_add_u32 s18, s64, 0x4000
	s_addc_u32 s19, s65, 0
	s_mov_b32 m0, s43
	ds_read_b128 v[192:195], v154 offset:32768
	ds_read_b128 v[200:203], v154 offset:33792
	ds_read_b128 v[204:207], v154 offset:34816
	ds_read_b128 v[208:211], v154 offset:35840
	ds_read_b128 v[212:215], v154 offset:36864
	ds_read_b128 v[216:219], v154 offset:37888
	ds_read_b128 v[220:223], v154 offset:38912
	ds_read_b128 v[224:227], v154 offset:39936
	global_load_lds_dwordx4 v130, s[18:19] sc1
	s_mov_b32 m0, s44
	s_nop 0
	global_load_lds_dwordx4 v128, s[18:19] sc1
	s_waitcnt vmcnt(8)
	s_waitcnt lgkmcnt(0)
	s_setprio 1
	s_barrier
	v_mfma_f32_16x16x32_bf16 v[116:119], v[156:159], v[192:195], v[116:119]
	v_mfma_f32_16x16x32_bf16 v[108:111], v[164:167], v[192:195], v[108:111]
	v_mfma_f32_16x16x32_bf16 v[100:103], v[156:159], v[204:207], v[100:103]
	v_mfma_f32_16x16x32_bf16 v[92:95], v[164:167], v[204:207], v[92:95]
	v_mfma_f32_16x16x32_bf16 v[84:87], v[156:159], v[212:215], v[84:87]
	v_mfma_f32_16x16x32_bf16 v[76:79], v[164:167], v[212:215], v[76:79]
	v_mfma_f32_16x16x32_bf16 v[60:63], v[156:159], v[220:223], v[60:63]
	v_mfma_f32_16x16x32_bf16 v[52:55], v[164:167], v[220:223], v[52:55]
	v_mfma_f32_16x16x32_bf16 v[116:119], v[160:163], v[200:203], v[116:119]
	v_mfma_f32_16x16x32_bf16 v[108:111], v[168:171], v[200:203], v[108:111]
	v_mfma_f32_16x16x32_bf16 v[100:103], v[160:163], v[208:211], v[100:103]
	v_mfma_f32_16x16x32_bf16 v[92:95], v[168:171], v[208:211], v[92:95]
	v_mfma_f32_16x16x32_bf16 v[84:87], v[160:163], v[216:219], v[84:87]
	v_mfma_f32_16x16x32_bf16 v[76:79], v[168:171], v[216:219], v[76:79]
	v_mfma_f32_16x16x32_bf16 v[60:63], v[160:163], v[224:227], v[60:63]
	v_mfma_f32_16x16x32_bf16 v[52:55], v[168:171], v[224:227], v[52:55]
	v_mfma_f32_16x16x32_bf16 v[124:127], v[172:175], v[192:195], v[124:127]
	v_mfma_f32_16x16x32_bf16 v[120:123], v[180:183], v[192:195], v[120:123]
	v_mfma_f32_16x16x32_bf16 v[112:115], v[172:175], v[204:207], v[112:115]
	v_mfma_f32_16x16x32_bf16 v[104:107], v[180:183], v[204:207], v[104:107]
	v_mfma_f32_16x16x32_bf16 v[96:99], v[172:175], v[212:215], v[96:99]
	v_mfma_f32_16x16x32_bf16 v[88:91], v[180:183], v[212:215], v[88:91]
	v_mfma_f32_16x16x32_bf16 v[80:83], v[172:175], v[220:223], v[80:83]
	v_mfma_f32_16x16x32_bf16 v[68:71], v[180:183], v[220:223], v[68:71]
	v_mfma_f32_16x16x32_bf16 v[124:127], v[176:179], v[200:203], v[124:127]
	v_mfma_f32_16x16x32_bf16 v[120:123], v[184:187], v[200:203], v[120:123]
	v_mfma_f32_16x16x32_bf16 v[112:115], v[176:179], v[208:211], v[112:115]
	v_mfma_f32_16x16x32_bf16 v[104:107], v[184:187], v[208:211], v[104:107]
	v_mfma_f32_16x16x32_bf16 v[96:99], v[176:179], v[216:219], v[96:99]
	v_mfma_f32_16x16x32_bf16 v[88:91], v[184:187], v[216:219], v[88:91]
	s_setprio 2
	s_barrier
	v_mfma_f32_16x16x32_bf16 v[80:83], v[176:179], v[224:227], v[80:83]
	v_mfma_f32_16x16x32_bf16 v[68:71], v[184:187], v[224:227], v[68:71]
	s_setprio 0
	s_add_u32 s18, s62, 0x8000
	s_addc_u32 s19, s63, 0
	s_add_i32 s64, s49, s36
	s_mov_b32 m0, s64
	ds_read_b128 v[192:195], v154 offset:49152
	ds_read_b128 v[200:203], v154 offset:50176
	ds_read_b128 v[204:207], v154 offset:51200
	ds_read_b128 v[208:211], v154 offset:52224
	ds_read_b128 v[212:215], v154 offset:53248
	ds_read_b128 v[216:219], v154 offset:54272
	ds_read_b128 v[220:223], v154 offset:55296
	ds_read_b128 v[224:227], v154 offset:56320
	global_load_lds_dwordx4 v132, s[18:19] sc1
	s_add_i32 m0, s64, 0x2000
	s_nop 0
	global_load_lds_dwordx4 v134, s[18:19] sc1
	s_add_u32 s18, s62, 0xc000
	s_addc_u32 s19, s63, 0
	s_add_i32 s62, s50, s36
	s_mov_b32 m0, s62
	s_nop 0
	global_load_lds_dwordx4 v132, s[18:19] sc1
	s_add_i32 m0, s62, 0x2000
	s_nop 0
	global_load_lds_dwordx4 v134, s[18:19] sc1
	s_mov_b32 m0, s7
	s_nop 0
	global_load_lds_dwordx4 v130, s[56:57] sc1
	s_mov_b32 m0, s45
	s_nop 0
	global_load_lds_dwordx4 v128, s[56:57] sc1
	s_waitcnt vmcnt(8)
	s_waitcnt lgkmcnt(0)
	s_setprio 1
	s_barrier
	v_mfma_f32_16x16x32_bf16 v[56:59], v[156:159], v[192:195], v[56:59]
	v_mfma_f32_16x16x32_bf16 v[44:47], v[164:167], v[192:195], v[44:47]
	v_mfma_f32_16x16x32_bf16 v[36:39], v[156:159], v[204:207], v[36:39]
	v_mfma_f32_16x16x32_bf16 v[28:31], v[164:167], v[204:207], v[28:31]
	v_mfma_f32_16x16x32_bf16 v[20:23], v[156:159], v[212:215], v[20:23]
	v_mfma_f32_16x16x32_bf16 v[12:15], v[164:167], v[212:215], v[12:15]
	v_mfma_f32_16x16x32_bf16 v[4:7], v[156:159], v[220:223], v[4:7]
	v_mfma_f32_16x16x32_bf16 v[0:3], v[164:167], v[220:223], v[0:3]
	v_mfma_f32_16x16x32_bf16 v[56:59], v[160:163], v[200:203], v[56:59]
	v_mfma_f32_16x16x32_bf16 v[44:47], v[168:171], v[200:203], v[44:47]
	v_mfma_f32_16x16x32_bf16 v[36:39], v[160:163], v[208:211], v[36:39]
	v_mfma_f32_16x16x32_bf16 v[28:31], v[168:171], v[208:211], v[28:31]
	v_mfma_f32_16x16x32_bf16 v[20:23], v[160:163], v[216:219], v[20:23]
	v_mfma_f32_16x16x32_bf16 v[12:15], v[168:171], v[216:219], v[12:15]
	v_mfma_f32_16x16x32_bf16 v[4:7], v[160:163], v[224:227], v[4:7]
	v_mfma_f32_16x16x32_bf16 v[0:3], v[168:171], v[224:227], v[0:3]
	v_mfma_f32_16x16x32_bf16 v[72:75], v[172:175], v[192:195], v[72:75]
	v_mfma_f32_16x16x32_bf16 v[64:67], v[180:183], v[192:195], v[64:67]
	v_mfma_f32_16x16x32_bf16 v[48:51], v[172:175], v[204:207], v[48:51]
	v_mfma_f32_16x16x32_bf16 v[40:43], v[180:183], v[204:207], v[40:43]
	v_mfma_f32_16x16x32_bf16 v[32:35], v[172:175], v[212:215], v[32:35]
	v_mfma_f32_16x16x32_bf16 v[24:27], v[180:183], v[212:215], v[24:27]
	v_mfma_f32_16x16x32_bf16 v[16:19], v[172:175], v[220:223], v[16:19]
	v_mfma_f32_16x16x32_bf16 v[8:11], v[180:183], v[220:223], v[8:11]
	v_mfma_f32_16x16x32_bf16 v[72:75], v[176:179], v[200:203], v[72:75]
	v_mfma_f32_16x16x32_bf16 v[64:67], v[184:187], v[200:203], v[64:67]
	v_mfma_f32_16x16x32_bf16 v[48:51], v[176:179], v[208:211], v[48:51]
	v_mfma_f32_16x16x32_bf16 v[40:43], v[184:187], v[208:211], v[40:43]
	v_mfma_f32_16x16x32_bf16 v[32:35], v[176:179], v[216:219], v[32:35]
	v_mfma_f32_16x16x32_bf16 v[24:27], v[184:187], v[216:219], v[24:27]
	s_setprio 2
	s_barrier
	v_mfma_f32_16x16x32_bf16 v[16:19], v[176:179], v[224:227], v[16:19]
	v_mfma_f32_16x16x32_bf16 v[8:11], v[184:187], v[224:227], v[8:11]
	s_setprio 0
	s_add_i32 s78, s78, 2
	s_add_u32 s76, s76, 0x10000
	s_addc_u32 s77, s77, 0
	s_cmp_gt_u32 s78, 13
	s_mov_b64 s[18:19], s[40:41]
	s_cbranch_scc0 .LBB0_1093
	s_cmp_eq_u32 s54, s59
	s_cbranch_scc1 .Lemb7_last
	s_mov_b32 s98, s54
	s_mov_b32 s54, s35
	s_add_i32 s35, s35, 1
	s_cmp_lt_u32 s35, s12
	s_mov_b64 s[40:41], s[16:17]
	s_mov_b32 s16, s61
	s_cselect_b64 s[56:57], -1, 0
	s_add_i32 s61, s35, s6
	s_mov_b64 s[18:19], s[0:1]
	s_and_b64 s[0:1], s[56:57], exec
	s_cselect_b32 s0, s58, s58
	s_cselect_b32 s16, s61, s16
	s_ashr_i32 s1, s0, 31
	s_lshl_b64 s[0:1], s[0:1], 19
	s_add_u32 s0, s60, s0
	s_addc_u32 s1, s33, s1
	s_and_b64 s[62:63], s[56:57], exec
	s_cselect_b32 s55, s1, s19
	s_cselect_b32 s69, s0, s18
	s_ashr_i32 s17, s16, 31
	s_lshl_b64 s[16:17], s[16:17], 19
	s_add_u32 s16, s66, s16
	s_addc_u32 s17, s67, s17
	s_and_b64 s[56:57], s[56:57], exec
	s_cselect_b32 s70, s17, s41
	s_cselect_b32 s71, s16, s40
	s_add_u32 s76, s40, 0x10000
	s_addc_u32 s77, s41, 0
	s_mov_b32 s78, -2
	v_add_u32_e32 v155, s47, v148
	ds_read_b128 v[156:159], v155
	ds_read_b128 v[160:163], v155 offset:1024
	ds_read_b128 v[164:167], v155 offset:2048
	ds_read_b128 v[168:171], v155 offset:3072
	v_add_u32_e32 v155, s48, v148
	ds_read_b128 v[172:175], v155
	ds_read_b128 v[176:179], v155 offset:1024
	ds_read_b128 v[180:183], v155 offset:2048
	ds_read_b128 v[184:187], v155 offset:3072
	s_add_u32 s40, s18, 0x10000
	s_addc_u32 s41, s19, 0
	s_cmp_eq_u32 s78, 12
	s_cselect_b32 s64, s69, s40
	s_cselect_b32 s65, s55, s41
	s_cselect_b32 s62, s71, s76
	s_cselect_b32 s63, s70, s77
	s_add_u32 s56, s64, 0x8000
	s_addc_u32 s57, s65, 0
	s_add_i32 m0, s37, 0xc000
	ds_read_b128 v[192:195], v154
	ds_read_b128 v[200:203], v154 offset:1024
	ds_read_b128 v[204:207], v154 offset:2048
	ds_read_b128 v[208:211], v154 offset:3072
	ds_read_b128 v[212:215], v154 offset:4096
	ds_read_b128 v[216:219], v154 offset:5120
	ds_read_b128 v[220:223], v154 offset:6144
	ds_read_b128 v[224:227], v154 offset:7168
	v_lshl_add_u32 v133, s98, 10, v153
	ds_read_b32 v228, v133
	ds_read_b32 v229, v133 offset:64
	ds_read_b32 v230, v133 offset:128
	ds_read_b32 v231, v133 offset:192
	global_load_lds_dwordx4 v144, s[18:19] sc1
	s_add_i32 m0, s37, 0xe000
	s_nop 0
	global_load_lds_dwordx4 v146, s[18:19] sc1
	s_waitcnt vmcnt(8)
	s_waitcnt lgkmcnt(0)
	s_setprio 1
	s_barrier
	s_add_i32 s99, s98, s6
	s_lshl_b32 s99, s99, 15
	s_or_b32 s99, s99, s51
	s_and_b32 s99, s99, 0xffffc000
	s_add_i32 s100, s99, s46
	v_mul_f32_e32 v248, 0xbfb8aa3b, v228
	v_mul_f32_e32 v249, v228, v228
	v_rcp_f32_e32 v250, v249
	v_pk_mul_f32 v[232:233], v[116:117], v[248:249] op_sel_hi:[1,0]
	v_pk_mul_f32 v[234:235], v[118:119], v[248:249] op_sel_hi:[1,0]
	v_pk_mul_f32 v[236:237], v[108:109], v[248:249] op_sel_hi:[1,0]
	v_pk_mul_f32 v[238:239], v[110:111], v[248:249] op_sel_hi:[1,0]
	v_pk_mul_f32 v[240:241], v[116:117], v[124:125]
	v_pk_mul_f32 v[242:243], v[118:119], v[126:127]
	v_pk_mul_f32 v[244:245], v[108:109], v[120:121]
	v_pk_mul_f32 v[246:247], v[110:111], v[122:123]
	v_exp_f32_e32 v232, v232
	v_exp_f32_e32 v233, v233
	v_exp_f32_e32 v234, v234
	v_exp_f32_e32 v235, v235
	v_mfma_f32_16x16x32_bf16 v[116:119], v[156:159], v[192:195], 0
	v_exp_f32_e32 v236, v236
	v_exp_f32_e32 v237, v237
	v_exp_f32_e32 v238, v238
	v_exp_f32_e32 v239, v239
	v_mfma_f32_16x16x32_bf16 v[108:111], v[164:167], v[192:195], 0
	v_fma_f32 v232, v232, v250, v250
	v_fma_f32 v233, v233, v250, v250
	v_fma_f32 v234, v234, v250, v250
	v_fma_f32 v235, v235, v250, v250
	v_mfma_f32_16x16x32_bf16 v[124:127], v[172:175], v[192:195], 0
	v_fma_f32 v236, v236, v250, v250
	v_fma_f32 v237, v237, v250, v250
	v_fma_f32 v238, v238, v250, v250
	v_fma_f32 v239, v239, v250, v250
	v_mfma_f32_16x16x32_bf16 v[120:123], v[180:183], v[192:195], 0
	v_rcp_f32_e32 v232, v232
	v_rcp_f32_e32 v233, v233
	v_rcp_f32_e32 v234, v234
	v_rcp_f32_e32 v235, v235
	v_mfma_f32_16x16x32_bf16 v[116:119], v[160:163], v[200:203], v[116:119]
	v_rcp_f32_e32 v236, v236
	v_rcp_f32_e32 v237, v237
	v_rcp_f32_e32 v238, v238
	v_rcp_f32_e32 v239, v239
	v_mfma_f32_16x16x32_bf16 v[108:111], v[168:171], v[200:203], v[108:111]
	v_or_b32_e32 v251, s100, v137
	v_lshlrev_b32_e32 v251, 1, v251
	v_pk_mul_f32 v[240:241], v[240:241], v[232:233]
	v_pk_mul_f32 v[242:243], v[242:243], v[234:235]
	v_mfma_f32_16x16x32_bf16 v[124:127], v[176:179], v[200:203], v[124:127]
	v_pk_mul_f32 v[244:245], v[244:245], v[236:237]
	v_pk_mul_f32 v[246:247], v[246:247], v[238:239]
	v_cvt_pk_bf16_f32 v232, v240, v241
	v_cvt_pk_bf16_f32 v233, v242, v243
	v_mfma_f32_16x16x32_bf16 v[120:123], v[184:187], v[200:203], v[120:123]
	v_cvt_pk_bf16_f32 v234, v244, v245
	v_cvt_pk_bf16_f32 v235, v246, v247
	buffer_store_dwordx4 v[232:235], v251, s[72:75], 0 offen sc1
	v_mul_f32_e32 v248, 0xbfb8aa3b, v229
	v_mul_f32_e32 v249, v229, v229
	v_rcp_f32_e32 v250, v249
	v_pk_mul_f32 v[232:233], v[100:101], v[248:249] op_sel_hi:[1,0]
	v_pk_mul_f32 v[234:235], v[102:103], v[248:249] op_sel_hi:[1,0]
	v_pk_mul_f32 v[236:237], v[92:93], v[248:249] op_sel_hi:[1,0]
	v_pk_mul_f32 v[238:239], v[94:95], v[248:249] op_sel_hi:[1,0]
	v_pk_mul_f32 v[240:241], v[100:101], v[112:113]
	v_pk_mul_f32 v[242:243], v[102:103], v[114:115]
	v_pk_mul_f32 v[244:245], v[92:93], v[104:105]
	v_pk_mul_f32 v[246:247], v[94:95], v[106:107]
	v_exp_f32_e32 v232, v232
	v_exp_f32_e32 v233, v233
	v_exp_f32_e32 v234, v234
	v_exp_f32_e32 v235, v235
	v_mfma_f32_16x16x32_bf16 v[100:103], v[156:159], v[204:207], 0
	v_exp_f32_e32 v236, v236
	v_exp_f32_e32 v237, v237
	v_exp_f32_e32 v238, v238
	v_exp_f32_e32 v239, v239
	v_mfma_f32_16x16x32_bf16 v[92:95], v[164:167], v[204:207], 0
	v_fma_f32 v232, v232, v250, v250
	v_fma_f32 v233, v233, v250, v250
	v_fma_f32 v234, v234, v250, v250
	v_fma_f32 v235, v235, v250, v250
	v_mfma_f32_16x16x32_bf16 v[112:115], v[172:175], v[204:207], 0
	v_fma_f32 v236, v236, v250, v250
	v_fma_f32 v237, v237, v250, v250
	v_fma_f32 v238, v238, v250, v250
	v_fma_f32 v239, v239, v250, v250
	v_mfma_f32_16x16x32_bf16 v[104:107], v[180:183], v[204:207], 0
	v_rcp_f32_e32 v232, v232
	v_rcp_f32_e32 v233, v233
	v_rcp_f32_e32 v234, v234
	v_rcp_f32_e32 v235, v235
	v_mfma_f32_16x16x32_bf16 v[100:103], v[160:163], v[208:211], v[100:103]
	v_rcp_f32_e32 v236, v236
	v_rcp_f32_e32 v237, v237
	v_rcp_f32_e32 v238, v238
	v_rcp_f32_e32 v239, v239
	v_mfma_f32_16x16x32_bf16 v[92:95], v[168:171], v[208:211], v[92:95]
	v_or_b32_e32 v251, s100, v139
	v_lshlrev_b32_e32 v251, 1, v251
	v_pk_mul_f32 v[240:241], v[240:241], v[232:233]
	v_pk_mul_f32 v[242:243], v[242:243], v[234:235]
	v_mfma_f32_16x16x32_bf16 v[112:115], v[176:179], v[208:211], v[112:115]
	v_pk_mul_f32 v[244:245], v[244:245], v[236:237]
	v_pk_mul_f32 v[246:247], v[246:247], v[238:239]
	v_cvt_pk_bf16_f32 v232, v240, v241
	v_cvt_pk_bf16_f32 v233, v242, v243
	v_mfma_f32_16x16x32_bf16 v[104:107], v[184:187], v[208:211], v[104:107]
	v_cvt_pk_bf16_f32 v234, v244, v245
	v_cvt_pk_bf16_f32 v235, v246, v247
	buffer_store_dwordx4 v[232:235], v251, s[72:75], 0 offen sc1
	v_mul_f32_e32 v248, 0xbfb8aa3b, v230
	v_mul_f32_e32 v249, v230, v230
	v_rcp_f32_e32 v250, v249
	v_pk_mul_f32 v[232:233], v[84:85], v[248:249] op_sel_hi:[1,0]
	v_pk_mul_f32 v[234:235], v[86:87], v[248:249] op_sel_hi:[1,0]
	v_pk_mul_f32 v[236:237], v[76:77], v[248:249] op_sel_hi:[1,0]
	v_pk_mul_f32 v[238:239], v[78:79], v[248:249] op_sel_hi:[1,0]
	v_pk_mul_f32 v[240:241], v[84:85], v[96:97]
	v_pk_mul_f32 v[242:243], v[86:87], v[98:99]
	v_pk_mul_f32 v[244:245], v[76:77], v[88:89]
	v_pk_mul_f32 v[246:247], v[78:79], v[90:91]
	v_exp_f32_e32 v232, v232
	v_exp_f32_e32 v233, v233
	v_exp_f32_e32 v234, v234
	v_exp_f32_e32 v235, v235
	v_mfma_f32_16x16x32_bf16 v[84:87], v[156:159], v[212:215], 0
	v_exp_f32_e32 v236, v236
	v_exp_f32_e32 v237, v237
	v_exp_f32_e32 v238, v238
	v_exp_f32_e32 v239, v239
	v_mfma_f32_16x16x32_bf16 v[76:79], v[164:167], v[212:215], 0
	v_fma_f32 v232, v232, v250, v250
	v_fma_f32 v233, v233, v250, v250
	v_fma_f32 v234, v234, v250, v250
	v_fma_f32 v235, v235, v250, v250
	v_mfma_f32_16x16x32_bf16 v[96:99], v[172:175], v[212:215], 0
	v_fma_f32 v236, v236, v250, v250
	v_fma_f32 v237, v237, v250, v250
	v_fma_f32 v238, v238, v250, v250
	v_fma_f32 v239, v239, v250, v250
	v_mfma_f32_16x16x32_bf16 v[88:91], v[180:183], v[212:215], 0
	v_rcp_f32_e32 v232, v232
	v_rcp_f32_e32 v233, v233
	v_rcp_f32_e32 v234, v234
	v_rcp_f32_e32 v235, v235
	v_mfma_f32_16x16x32_bf16 v[84:87], v[160:163], v[216:219], v[84:87]
	v_rcp_f32_e32 v236, v236
	v_rcp_f32_e32 v237, v237
	v_rcp_f32_e32 v238, v238
	v_rcp_f32_e32 v239, v239
	v_mfma_f32_16x16x32_bf16 v[76:79], v[168:171], v[216:219], v[76:79]
	v_or_b32_e32 v251, s100, v141
	v_lshlrev_b32_e32 v251, 1, v251
	v_pk_mul_f32 v[240:241], v[240:241], v[232:233]
	v_pk_mul_f32 v[242:243], v[242:243], v[234:235]
	v_mfma_f32_16x16x32_bf16 v[96:99], v[176:179], v[216:219], v[96:99]
	v_pk_mul_f32 v[244:245], v[244:245], v[236:237]
	v_pk_mul_f32 v[246:247], v[246:247], v[238:239]
	v_cvt_pk_bf16_f32 v232, v240, v241
	v_cvt_pk_bf16_f32 v233, v242, v243
	v_mfma_f32_16x16x32_bf16 v[88:91], v[184:187], v[216:219], v[88:91]
	v_cvt_pk_bf16_f32 v234, v244, v245
	v_cvt_pk_bf16_f32 v235, v246, v247
	buffer_store_dwordx4 v[232:235], v251, s[72:75], 0 offen sc1
	v_mul_f32_e32 v248, 0xbfb8aa3b, v231
	v_mul_f32_e32 v249, v231, v231
	v_rcp_f32_e32 v250, v249
	v_pk_mul_f32 v[232:233], v[60:61], v[248:249] op_sel_hi:[1,0]
	v_pk_mul_f32 v[234:235], v[62:63], v[248:249] op_sel_hi:[1,0]
	v_pk_mul_f32 v[236:237], v[52:53], v[248:249] op_sel_hi:[1,0]
	v_pk_mul_f32 v[238:239], v[54:55], v[248:249] op_sel_hi:[1,0]
	v_pk_mul_f32 v[240:241], v[60:61], v[80:81]
	v_pk_mul_f32 v[242:243], v[62:63], v[82:83]
	v_pk_mul_f32 v[244:245], v[52:53], v[68:69]
	v_pk_mul_f32 v[246:247], v[54:55], v[70:71]
	v_exp_f32_e32 v232, v232
	v_exp_f32_e32 v233, v233
	v_exp_f32_e32 v234, v234
	v_exp_f32_e32 v235, v235
	v_mfma_f32_16x16x32_bf16 v[60:63], v[156:159], v[220:223], 0
	v_exp_f32_e32 v236, v236
	v_exp_f32_e32 v237, v237
	v_exp_f32_e32 v238, v238
	v_exp_f32_e32 v239, v239
	v_mfma_f32_16x16x32_bf16 v[52:55], v[164:167], v[220:223], 0
	v_fma_f32 v232, v232, v250, v250
	v_fma_f32 v233, v233, v250, v250
	v_fma_f32 v234, v234, v250, v250
	v_fma_f32 v235, v235, v250, v250
	v_mfma_f32_16x16x32_bf16 v[80:83], v[172:175], v[220:223], 0
	v_fma_f32 v236, v236, v250, v250
	v_fma_f32 v237, v237, v250, v250
	v_fma_f32 v238, v238, v250, v250
	v_fma_f32 v239, v239, v250, v250
	v_mfma_f32_16x16x32_bf16 v[68:71], v[180:183], v[220:223], 0
	v_rcp_f32_e32 v232, v232
	v_rcp_f32_e32 v233, v233
	v_rcp_f32_e32 v234, v234
	v_rcp_f32_e32 v235, v235
	v_mfma_f32_16x16x32_bf16 v[60:63], v[160:163], v[224:227], v[60:63]
	v_rcp_f32_e32 v236, v236
	v_rcp_f32_e32 v237, v237
	v_rcp_f32_e32 v238, v238
	v_rcp_f32_e32 v239, v239
	v_mfma_f32_16x16x32_bf16 v[52:55], v[168:171], v[224:227], v[52:55]
	v_or_b32_e32 v251, s100, v143
	v_lshlrev_b32_e32 v251, 1, v251
	v_pk_mul_f32 v[240:241], v[240:241], v[232:233]
	v_pk_mul_f32 v[242:243], v[242:243], v[234:235]
	v_pk_mul_f32 v[244:245], v[244:245], v[236:237]
	v_pk_mul_f32 v[246:247], v[246:247], v[238:239]
	v_cvt_pk_bf16_f32 v232, v240, v241
	v_cvt_pk_bf16_f32 v233, v242, v243
	v_cvt_pk_bf16_f32 v234, v244, v245
	v_cvt_pk_bf16_f32 v235, v246, v247
	buffer_store_dwordx4 v[232:235], v251, s[72:75], 0 offen sc1
	s_setprio 2
	s_barrier
	v_mfma_f32_16x16x32_bf16 v[80:83], v[176:179], v[224:227], v[80:83]
	v_mfma_f32_16x16x32_bf16 v[68:71], v[184:187], v[224:227], v[68:71]
	s_setprio 0
	s_add_i32 s18, s47, s36
	s_mov_b32 m0, s18
	ds_read_b128 v[192:195], v154 offset:16384
	ds_read_b128 v[200:203], v154 offset:17408
	ds_read_b128 v[204:207], v154 offset:18432
	ds_read_b128 v[208:211], v154 offset:19456
	ds_read_b128 v[212:215], v154 offset:20480
	ds_read_b128 v[216:219], v154 offset:21504
	ds_read_b128 v[220:223], v154 offset:22528
	ds_read_b128 v[224:227], v154 offset:23552
	ds_read_b32 v228, v133 offset:512
	ds_read_b32 v229, v133 offset:576
	ds_read_b32 v230, v133 offset:640
	ds_read_b32 v231, v133 offset:704
	global_load_lds_dwordx4 v132, s[62:63] sc1
	s_add_i32 m0, s18, 0x2000
	s_add_u32 s18, s62, 0x4000
	s_addc_u32 s19, s63, 0
	s_add_i32 s79, s48, s36
	global_load_lds_dwordx4 v134, s[62:63] sc1
	s_mov_b32 m0, s79
	s_nop 0
	global_load_lds_dwordx4 v132, s[18:19] sc1
	s_add_i32 m0, s79, 0x2000
	s_nop 0
	global_load_lds_dwordx4 v134, s[18:19] sc1
	s_mov_b32 m0, s37
	s_nop 0
	global_load_lds_dwordx4 v130, s[64:65] sc1
	s_mov_b32 m0, s42
	s_nop 0
	global_load_lds_dwordx4 v128, s[64:65] sc1
	s_waitcnt vmcnt(12)
	s_waitcnt lgkmcnt(0)
	s_setprio 1
	s_barrier
	v_mul_f32_e32 v248, 0xbfb8aa3b, v228
	v_mul_f32_e32 v249, v228, v228
	v_rcp_f32_e32 v250, v249
	v_pk_mul_f32 v[232:233], v[56:57], v[248:249] op_sel_hi:[1,0]
	v_pk_mul_f32 v[234:235], v[58:59], v[248:249] op_sel_hi:[1,0]
	v_pk_mul_f32 v[236:237], v[44:45], v[248:249] op_sel_hi:[1,0]
	v_pk_mul_f32 v[238:239], v[46:47], v[248:249] op_sel_hi:[1,0]
	v_pk_mul_f32 v[240:241], v[56:57], v[72:73]
	v_pk_mul_f32 v[242:243], v[58:59], v[74:75]
	v_pk_mul_f32 v[244:245], v[44:45], v[64:65]
	v_pk_mul_f32 v[246:247], v[46:47], v[66:67]
	v_exp_f32_e32 v232, v232
	v_exp_f32_e32 v233, v233
	v_exp_f32_e32 v234, v234
	v_exp_f32_e32 v235, v235
	v_mfma_f32_16x16x32_bf16 v[56:59], v[156:159], v[192:195], 0
	v_exp_f32_e32 v236, v236
	v_exp_f32_e32 v237, v237
	v_exp_f32_e32 v238, v238
	v_exp_f32_e32 v239, v239
	v_mfma_f32_16x16x32_bf16 v[44:47], v[164:167], v[192:195], 0
	v_fma_f32 v232, v232, v250, v250
	v_fma_f32 v233, v233, v250, v250
	v_fma_f32 v234, v234, v250, v250
	v_fma_f32 v235, v235, v250, v250
	v_mfma_f32_16x16x32_bf16 v[72:75], v[172:175], v[192:195], 0
	v_fma_f32 v236, v236, v250, v250
	v_fma_f32 v237, v237, v250, v250
	v_fma_f32 v238, v238, v250, v250
	v_fma_f32 v239, v239, v250, v250
	v_mfma_f32_16x16x32_bf16 v[64:67], v[180:183], v[192:195], 0
	v_rcp_f32_e32 v232, v232
	v_rcp_f32_e32 v233, v233
	v_rcp_f32_e32 v234, v234
	v_rcp_f32_e32 v235, v235
	v_mfma_f32_16x16x32_bf16 v[56:59], v[160:163], v[200:203], v[56:59]
	v_rcp_f32_e32 v236, v236
	v_rcp_f32_e32 v237, v237
	v_rcp_f32_e32 v238, v238
	v_rcp_f32_e32 v239, v239
	v_mfma_f32_16x16x32_bf16 v[44:47], v[168:171], v[200:203], v[44:47]
	v_add_u32_e32 v251, s99, v136
	v_or_b32_e32 v251, v251, v149
	v_lshlrev_b32_e32 v251, 1, v251
	v_pk_mul_f32 v[240:241], v[240:241], v[232:233]
	v_mfma_f32_16x16x32_bf16 v[72:75], v[176:179], v[200:203], v[72:75]
	v_pk_mul_f32 v[242:243], v[242:243], v[234:235]
	v_pk_mul_f32 v[244:245], v[244:245], v[236:237]
	v_pk_mul_f32 v[246:247], v[246:247], v[238:239]
	v_cvt_pk_bf16_f32 v232, v240, v241
	v_mfma_f32_16x16x32_bf16 v[64:67], v[184:187], v[200:203], v[64:67]
	v_cvt_pk_bf16_f32 v233, v242, v243
	v_cvt_pk_bf16_f32 v234, v244, v245
	v_cvt_pk_bf16_f32 v235, v246, v247
	buffer_store_dwordx4 v[232:235], v251, s[72:75], 0 offen sc1
	v_mul_f32_e32 v248, 0xbfb8aa3b, v229
	v_mul_f32_e32 v249, v229, v229
	v_rcp_f32_e32 v250, v249
	v_pk_mul_f32 v[232:233], v[36:37], v[248:249] op_sel_hi:[1,0]
	v_pk_mul_f32 v[234:235], v[38:39], v[248:249] op_sel_hi:[1,0]
	v_pk_mul_f32 v[236:237], v[28:29], v[248:249] op_sel_hi:[1,0]
	v_pk_mul_f32 v[238:239], v[30:31], v[248:249] op_sel_hi:[1,0]
	v_pk_mul_f32 v[240:241], v[36:37], v[48:49]
	v_pk_mul_f32 v[242:243], v[38:39], v[50:51]
	v_pk_mul_f32 v[244:245], v[28:29], v[40:41]
	v_pk_mul_f32 v[246:247], v[30:31], v[42:43]
	v_exp_f32_e32 v232, v232
	v_exp_f32_e32 v233, v233
	v_exp_f32_e32 v234, v234
	v_exp_f32_e32 v235, v235
	v_mfma_f32_16x16x32_bf16 v[36:39], v[156:159], v[204:207], 0
	v_exp_f32_e32 v236, v236
	v_exp_f32_e32 v237, v237
	v_exp_f32_e32 v238, v238
	v_exp_f32_e32 v239, v239
	v_mfma_f32_16x16x32_bf16 v[28:31], v[164:167], v[204:207], 0
	v_fma_f32 v232, v232, v250, v250
	v_fma_f32 v233, v233, v250, v250
	v_fma_f32 v234, v234, v250, v250
	v_fma_f32 v235, v235, v250, v250
	v_mfma_f32_16x16x32_bf16 v[48:51], v[172:175], v[204:207], 0
	v_fma_f32 v236, v236, v250, v250
	v_fma_f32 v237, v237, v250, v250
	v_fma_f32 v238, v238, v250, v250
	v_fma_f32 v239, v239, v250, v250
	v_mfma_f32_16x16x32_bf16 v[40:43], v[180:183], v[204:207], 0
	v_rcp_f32_e32 v232, v232
	v_rcp_f32_e32 v233, v233
	v_rcp_f32_e32 v234, v234
	v_rcp_f32_e32 v235, v235
	v_mfma_f32_16x16x32_bf16 v[36:39], v[160:163], v[208:211], v[36:39]
	v_rcp_f32_e32 v236, v236
	v_rcp_f32_e32 v237, v237
	v_rcp_f32_e32 v238, v238
	v_rcp_f32_e32 v239, v239
	v_mfma_f32_16x16x32_bf16 v[28:31], v[168:171], v[208:211], v[28:31]
	v_add_u32_e32 v251, s99, v138
	v_or_b32_e32 v251, v251, v150
	v_lshlrev_b32_e32 v251, 1, v251
	v_pk_mul_f32 v[240:241], v[240:241], v[232:233]
	v_mfma_f32_16x16x32_bf16 v[48:51], v[176:179], v[208:211], v[48:51]
	v_pk_mul_f32 v[242:243], v[242:243], v[234:235]
	v_pk_mul_f32 v[244:245], v[244:245], v[236:237]
	v_pk_mul_f32 v[246:247], v[246:247], v[238:239]
	v_cvt_pk_bf16_f32 v232, v240, v241
	v_mfma_f32_16x16x32_bf16 v[40:43], v[184:187], v[208:211], v[40:43]
	v_cvt_pk_bf16_f32 v233, v242, v243
	v_cvt_pk_bf16_f32 v234, v244, v245
	v_cvt_pk_bf16_f32 v235, v246, v247
	buffer_store_dwordx4 v[232:235], v251, s[72:75], 0 offen sc1
	v_mul_f32_e32 v248, 0xbfb8aa3b, v230
	v_mul_f32_e32 v249, v230, v230
	v_rcp_f32_e32 v250, v249
	v_pk_mul_f32 v[232:233], v[20:21], v[248:249] op_sel_hi:[1,0]
	v_pk_mul_f32 v[234:235], v[22:23], v[248:249] op_sel_hi:[1,0]
	v_pk_mul_f32 v[236:237], v[12:13], v[248:249] op_sel_hi:[1,0]
	v_pk_mul_f32 v[238:239], v[14:15], v[248:249] op_sel_hi:[1,0]
	v_pk_mul_f32 v[240:241], v[20:21], v[32:33]
	v_pk_mul_f32 v[242:243], v[22:23], v[34:35]
	v_pk_mul_f32 v[244:245], v[12:13], v[24:25]
	v_pk_mul_f32 v[246:247], v[14:15], v[26:27]
	v_exp_f32_e32 v232, v232
	v_exp_f32_e32 v233, v233
	v_exp_f32_e32 v234, v234
	v_exp_f32_e32 v235, v235
	v_mfma_f32_16x16x32_bf16 v[20:23], v[156:159], v[212:215], 0
	v_exp_f32_e32 v236, v236
	v_exp_f32_e32 v237, v237
	v_exp_f32_e32 v238, v238
	v_exp_f32_e32 v239, v239
	v_mfma_f32_16x16x32_bf16 v[12:15], v[164:167], v[212:215], 0
	v_fma_f32 v232, v232, v250, v250
	v_fma_f32 v233, v233, v250, v250
	v_fma_f32 v234, v234, v250, v250
	v_fma_f32 v235, v235, v250, v250
	v_mfma_f32_16x16x32_bf16 v[32:35], v[172:175], v[212:215], 0
	v_fma_f32 v236, v236, v250, v250
	v_fma_f32 v237, v237, v250, v250
	v_fma_f32 v238, v238, v250, v250
	v_fma_f32 v239, v239, v250, v250
	v_mfma_f32_16x16x32_bf16 v[24:27], v[180:183], v[212:215], 0
	v_rcp_f32_e32 v232, v232
	v_rcp_f32_e32 v233, v233
	v_rcp_f32_e32 v234, v234
	v_rcp_f32_e32 v235, v235
	v_mfma_f32_16x16x32_bf16 v[20:23], v[160:163], v[216:219], v[20:23]
	v_rcp_f32_e32 v236, v236
	v_rcp_f32_e32 v237, v237
	v_rcp_f32_e32 v238, v238
	v_rcp_f32_e32 v239, v239
	v_mfma_f32_16x16x32_bf16 v[12:15], v[168:171], v[216:219], v[12:15]
	v_add_u32_e32 v251, s99, v140
	v_or_b32_e32 v251, v251, v151
	v_lshlrev_b32_e32 v251, 1, v251
	v_pk_mul_f32 v[240:241], v[240:241], v[232:233]
	v_mfma_f32_16x16x32_bf16 v[32:35], v[176:179], v[216:219], v[32:35]
	v_pk_mul_f32 v[242:243], v[242:243], v[234:235]
	v_pk_mul_f32 v[244:245], v[244:245], v[236:237]
	v_pk_mul_f32 v[246:247], v[246:247], v[238:239]
	v_cvt_pk_bf16_f32 v232, v240, v241
	v_mfma_f32_16x16x32_bf16 v[24:27], v[184:187], v[216:219], v[24:27]
	v_cvt_pk_bf16_f32 v233, v242, v243
	v_cvt_pk_bf16_f32 v234, v244, v245
	v_cvt_pk_bf16_f32 v235, v246, v247
	buffer_store_dwordx4 v[232:235], v251, s[72:75], 0 offen sc1
	v_mul_f32_e32 v248, 0xbfb8aa3b, v231
	v_mul_f32_e32 v249, v231, v231
	v_rcp_f32_e32 v250, v249
	v_pk_mul_f32 v[232:233], v[4:5], v[248:249] op_sel_hi:[1,0]
	v_pk_mul_f32 v[234:235], v[6:7], v[248:249] op_sel_hi:[1,0]
	v_pk_mul_f32 v[236:237], v[0:1], v[248:249] op_sel_hi:[1,0]
	v_pk_mul_f32 v[238:239], v[2:3], v[248:249] op_sel_hi:[1,0]
	v_pk_mul_f32 v[240:241], v[4:5], v[16:17]
	v_pk_mul_f32 v[242:243], v[6:7], v[18:19]
	v_pk_mul_f32 v[244:245], v[0:1], v[8:9]
	v_pk_mul_f32 v[246:247], v[2:3], v[10:11]
	v_exp_f32_e32 v232, v232
	v_exp_f32_e32 v233, v233
	v_exp_f32_e32 v234, v234
	v_exp_f32_e32 v235, v235
	v_mfma_f32_16x16x32_bf16 v[4:7], v[156:159], v[220:223], 0
	v_exp_f32_e32 v236, v236
	v_exp_f32_e32 v237, v237
	v_exp_f32_e32 v238, v238
	v_exp_f32_e32 v239, v239
	v_mfma_f32_16x16x32_bf16 v[0:3], v[164:167], v[220:223], 0
	v_fma_f32 v232, v232, v250, v250
	v_fma_f32 v233, v233, v250, v250
	v_fma_f32 v234, v234, v250, v250
	v_fma_f32 v235, v235, v250, v250
	v_mfma_f32_16x16x32_bf16 v[16:19], v[172:175], v[220:223], 0
	v_fma_f32 v236, v236, v250, v250
	v_fma_f32 v237, v237, v250, v250
	v_fma_f32 v238, v238, v250, v250
	v_fma_f32 v239, v239, v250, v250
	v_mfma_f32_16x16x32_bf16 v[8:11], v[180:183], v[220:223], 0
	v_rcp_f32_e32 v232, v232
	v_rcp_f32_e32 v233, v233
	v_rcp_f32_e32 v234, v234
	v_rcp_f32_e32 v235, v235
	v_mfma_f32_16x16x32_bf16 v[4:7], v[160:163], v[224:227], v[4:7]
	v_rcp_f32_e32 v236, v236
	v_rcp_f32_e32 v237, v237
	v_rcp_f32_e32 v238, v238
	v_rcp_f32_e32 v239, v239
	v_mfma_f32_16x16x32_bf16 v[0:3], v[168:171], v[224:227], v[0:3]
	v_add_u32_e32 v251, s99, v142
	v_or_b32_e32 v251, v251, v152
	v_lshlrev_b32_e32 v251, 1, v251
	v_pk_mul_f32 v[240:241], v[240:241], v[232:233]
	v_pk_mul_f32 v[242:243], v[242:243], v[234:235]
	v_pk_mul_f32 v[244:245], v[244:245], v[236:237]
	v_pk_mul_f32 v[246:247], v[246:247], v[238:239]
	v_cvt_pk_bf16_f32 v232, v240, v241
	v_cvt_pk_bf16_f32 v233, v242, v243
	v_cvt_pk_bf16_f32 v234, v244, v245
	v_cvt_pk_bf16_f32 v235, v246, v247
	buffer_store_dwordx4 v[232:235], v251, s[72:75], 0 offen sc1
	s_setprio 2
	s_barrier
	v_mfma_f32_16x16x32_bf16 v[16:19], v[176:179], v[224:227], v[16:19]
	v_mfma_f32_16x16x32_bf16 v[8:11], v[184:187], v[224:227], v[8:11]
	s_setprio 0
	v_add_u32_e32 v155, s49, v148
	ds_read_b128 v[156:159], v155
	ds_read_b128 v[160:163], v155 offset:1024
	ds_read_b128 v[164:167], v155 offset:2048
	ds_read_b128 v[168:171], v155 offset:3072
	v_add_u32_e32 v155, s50, v148
	ds_read_b128 v[172:175], v155
	ds_read_b128 v[176:179], v155 offset:1024
	ds_read_b128 v[180:183], v155 offset:2048
	ds_read_b128 v[184:187], v155 offset:3072
	s_add_u32 s18, s64, 0x4000
	s_addc_u32 s19, s65, 0
	s_mov_b32 m0, s43
	ds_read_b128 v[192:195], v154 offset:32768
	ds_read_b128 v[200:203], v154 offset:33792
	ds_read_b128 v[204:207], v154 offset:34816
	ds_read_b128 v[208:211], v154 offset:35840
	ds_read_b128 v[212:215], v154 offset:36864
	ds_read_b128 v[216:219], v154 offset:37888
	ds_read_b128 v[220:223], v154 offset:38912
	ds_read_b128 v[224:227], v154 offset:39936
	global_load_lds_dwordx4 v130, s[18:19] sc1
	s_mov_b32 m0, s44
	s_nop 0
	global_load_lds_dwordx4 v128, s[18:19] sc1
	s_waitcnt vmcnt(16)
	s_waitcnt lgkmcnt(0)
	s_setprio 1
	s_barrier
	v_mfma_f32_16x16x32_bf16 v[116:119], v[156:159], v[192:195], v[116:119]
	v_mfma_f32_16x16x32_bf16 v[108:111], v[164:167], v[192:195], v[108:111]
	v_mfma_f32_16x16x32_bf16 v[100:103], v[156:159], v[204:207], v[100:103]
	v_mfma_f32_16x16x32_bf16 v[92:95], v[164:167], v[204:207], v[92:95]
	v_mfma_f32_16x16x32_bf16 v[84:87], v[156:159], v[212:215], v[84:87]
	v_mfma_f32_16x16x32_bf16 v[76:79], v[164:167], v[212:215], v[76:79]
	v_mfma_f32_16x16x32_bf16 v[60:63], v[156:159], v[220:223], v[60:63]
	v_mfma_f32_16x16x32_bf16 v[52:55], v[164:167], v[220:223], v[52:55]
	v_mfma_f32_16x16x32_bf16 v[116:119], v[160:163], v[200:203], v[116:119]
	v_mfma_f32_16x16x32_bf16 v[108:111], v[168:171], v[200:203], v[108:111]
	v_mfma_f32_16x16x32_bf16 v[100:103], v[160:163], v[208:211], v[100:103]
	v_mfma_f32_16x16x32_bf16 v[92:95], v[168:171], v[208:211], v[92:95]
	v_mfma_f32_16x16x32_bf16 v[84:87], v[160:163], v[216:219], v[84:87]
	v_mfma_f32_16x16x32_bf16 v[76:79], v[168:171], v[216:219], v[76:79]
	v_mfma_f32_16x16x32_bf16 v[60:63], v[160:163], v[224:227], v[60:63]
	v_mfma_f32_16x16x32_bf16 v[52:55], v[168:171], v[224:227], v[52:55]
	v_mfma_f32_16x16x32_bf16 v[124:127], v[172:175], v[192:195], v[124:127]
	v_mfma_f32_16x16x32_bf16 v[120:123], v[180:183], v[192:195], v[120:123]
	v_mfma_f32_16x16x32_bf16 v[112:115], v[172:175], v[204:207], v[112:115]
	v_mfma_f32_16x16x32_bf16 v[104:107], v[180:183], v[204:207], v[104:107]
	v_mfma_f32_16x16x32_bf16 v[96:99], v[172:175], v[212:215], v[96:99]
	v_mfma_f32_16x16x32_bf16 v[88:91], v[180:183], v[212:215], v[88:91]
	v_mfma_f32_16x16x32_bf16 v[80:83], v[172:175], v[220:223], v[80:83]
	v_mfma_f32_16x16x32_bf16 v[68:71], v[180:183], v[220:223], v[68:71]
	v_mfma_f32_16x16x32_bf16 v[124:127], v[176:179], v[200:203], v[124:127]
	v_mfma_f32_16x16x32_bf16 v[120:123], v[184:187], v[200:203], v[120:123]
	v_mfma_f32_16x16x32_bf16 v[112:115], v[176:179], v[208:211], v[112:115]
	v_mfma_f32_16x16x32_bf16 v[104:107], v[184:187], v[208:211], v[104:107]
	v_mfma_f32_16x16x32_bf16 v[96:99], v[176:179], v[216:219], v[96:99]
	v_mfma_f32_16x16x32_bf16 v[88:91], v[184:187], v[216:219], v[88:91]
	s_setprio 2
	s_barrier
	v_mfma_f32_16x16x32_bf16 v[80:83], v[176:179], v[224:227], v[80:83]
	v_mfma_f32_16x16x32_bf16 v[68:71], v[184:187], v[224:227], v[68:71]
	s_setprio 0
	s_add_u32 s18, s62, 0x8000
	s_addc_u32 s19, s63, 0
	s_add_i32 s64, s49, s36
	s_mov_b32 m0, s64
	ds_read_b128 v[192:195], v154 offset:49152
	ds_read_b128 v[200:203], v154 offset:50176
	ds_read_b128 v[204:207], v154 offset:51200
	ds_read_b128 v[208:211], v154 offset:52224
	ds_read_b128 v[212:215], v154 offset:53248
	ds_read_b128 v[216:219], v154 offset:54272
	ds_read_b128 v[220:223], v154 offset:55296
	ds_read_b128 v[224:227], v154 offset:56320
	global_load_lds_dwordx4 v132, s[18:19] sc1
	s_add_i32 m0, s64, 0x2000
	s_nop 0
	global_load_lds_dwordx4 v134, s[18:19] sc1
	s_add_u32 s18, s62, 0xc000
	s_addc_u32 s19, s63, 0
	s_add_i32 s62, s50, s36
	s_mov_b32 m0, s62
	s_nop 0
	global_load_lds_dwordx4 v132, s[18:19] sc1
	s_add_i32 m0, s62, 0x2000
	s_nop 0
	global_load_lds_dwordx4 v134, s[18:19] sc1
	s_mov_b32 m0, s7
	s_nop 0
	global_load_lds_dwordx4 v130, s[56:57] sc1
	s_mov_b32 m0, s45
	s_nop 0
	global_load_lds_dwordx4 v128, s[56:57] sc1
	s_waitcnt vmcnt(12)
	s_waitcnt lgkmcnt(0)
	s_setprio 1
	s_barrier
	v_mfma_f32_16x16x32_bf16 v[56:59], v[156:159], v[192:195], v[56:59]
	v_mfma_f32_16x16x32_bf16 v[44:47], v[164:167], v[192:195], v[44:47]
	v_mfma_f32_16x16x32_bf16 v[36:39], v[156:159], v[204:207], v[36:39]
	v_mfma_f32_16x16x32_bf16 v[28:31], v[164:167], v[204:207], v[28:31]
	v_mfma_f32_16x16x32_bf16 v[20:23], v[156:159], v[212:215], v[20:23]
	v_mfma_f32_16x16x32_bf16 v[12:15], v[164:167], v[212:215], v[12:15]
	v_mfma_f32_16x16x32_bf16 v[4:7], v[156:159], v[220:223], v[4:7]
	v_mfma_f32_16x16x32_bf16 v[0:3], v[164:167], v[220:223], v[0:3]
	v_mfma_f32_16x16x32_bf16 v[56:59], v[160:163], v[200:203], v[56:59]
	v_mfma_f32_16x16x32_bf16 v[44:47], v[168:171], v[200:203], v[44:47]
	v_mfma_f32_16x16x32_bf16 v[36:39], v[160:163], v[208:211], v[36:39]
	v_mfma_f32_16x16x32_bf16 v[28:31], v[168:171], v[208:211], v[28:31]
	v_mfma_f32_16x16x32_bf16 v[20:23], v[160:163], v[216:219], v[20:23]
	v_mfma_f32_16x16x32_bf16 v[12:15], v[168:171], v[216:219], v[12:15]
	v_mfma_f32_16x16x32_bf16 v[4:7], v[160:163], v[224:227], v[4:7]
	v_mfma_f32_16x16x32_bf16 v[0:3], v[168:171], v[224:227], v[0:3]
	v_mfma_f32_16x16x32_bf16 v[72:75], v[172:175], v[192:195], v[72:75]
	v_mfma_f32_16x16x32_bf16 v[64:67], v[180:183], v[192:195], v[64:67]
	v_mfma_f32_16x16x32_bf16 v[48:51], v[172:175], v[204:207], v[48:51]
	v_mfma_f32_16x16x32_bf16 v[40:43], v[180:183], v[204:207], v[40:43]
	v_mfma_f32_16x16x32_bf16 v[32:35], v[172:175], v[212:215], v[32:35]
	v_mfma_f32_16x16x32_bf16 v[24:27], v[180:183], v[212:215], v[24:27]
	v_mfma_f32_16x16x32_bf16 v[16:19], v[172:175], v[220:223], v[16:19]
	v_mfma_f32_16x16x32_bf16 v[8:11], v[180:183], v[220:223], v[8:11]
	v_mfma_f32_16x16x32_bf16 v[72:75], v[176:179], v[200:203], v[72:75]
	v_mfma_f32_16x16x32_bf16 v[64:67], v[184:187], v[200:203], v[64:67]
	v_mfma_f32_16x16x32_bf16 v[48:51], v[176:179], v[208:211], v[48:51]
	v_mfma_f32_16x16x32_bf16 v[40:43], v[184:187], v[208:211], v[40:43]
	v_mfma_f32_16x16x32_bf16 v[32:35], v[176:179], v[216:219], v[32:35]
	v_mfma_f32_16x16x32_bf16 v[24:27], v[184:187], v[216:219], v[24:27]
	s_setprio 2
	s_barrier
	v_mfma_f32_16x16x32_bf16 v[16:19], v[176:179], v[224:227], v[16:19]
	v_mfma_f32_16x16x32_bf16 v[8:11], v[184:187], v[224:227], v[8:11]
	s_setprio 0
	s_add_i32 s78, s78, 2
	s_add_u32 s76, s76, 0x10000
	s_addc_u32 s77, s77, 0
	s_cmp_gt_u32 s78, 13
	s_mov_b64 s[18:19], s[40:41]
	s_branch .LBB0_1093
